# local barrier after P7 without L1/L2 invalidate: the consumers' (P1, final norm) row loads use sc1 (L1 bypass) instead
# speedup vs baseline: 1.0174x; 1.0060x over previous
.LBB0_322:
	s_lshl_b64 s[18:19], s[18:19], 12
	v_lshlrev_b32_e32 v142, 2, v46
	s_waitcnt lgkmcnt(0)
	s_add_u32 s12, s12, s18
	v_ashrrev_i32_e32 v143, 31, v142
	s_addc_u32 s13, s13, s19
	v_lshl_add_u64 v[0:1], v[142:143], 2, s[12:13]
	global_load_dwordx4 v[62:65], v[0:1], off sc1
	global_load_dwordx4 v[34:37], v[0:1], off offset:1024 sc1
	global_load_dwordx4 v[14:17], v[0:1], off offset:2048 sc1
	s_nop 0
	global_load_dwordx4 v[0:3], v[0:1], off offset:3072 sc1
	v_readlane_b32 s18, v251, 35
	s_and_b64 vcc, exec, s[8:9]
	v_readlane_b32 s19, v251, 36
	s_mov_b64 s[12:13], s[44:45]
	s_cbranch_vccnz .LBB0_327
	v_readlane_b32 s12, v251, 11
	v_readlane_b32 s13, v251, 12
	s_andn2_b64 vcc, exec, s[12:13]
	s_mov_b64 s[18:19], -1
	s_cbranch_vccnz .LBB0_325
	s_load_dwordx2 s[12:13], s[10:11], 0x8
	s_mov_b64 s[18:19], 0

.LBB0_327:
	s_lshl_b64 s[18:19], s[18:19], 12
	s_waitcnt lgkmcnt(0)
	s_add_u32 s12, s12, s18
	s_addc_u32 s13, s13, s19
	v_lshl_add_u64 v[4:5], v[142:143], 2, s[12:13]
	global_load_dwordx4 v[78:81], v[4:5], off sc1
	global_load_dwordx4 v[42:45], v[4:5], off offset:1024 sc1
	global_load_dwordx4 v[22:25], v[4:5], off offset:2048 sc1
	s_nop 0
	global_load_dwordx4 v[4:7], v[4:5], off offset:3072 sc1
	v_readlane_b32 s18, v251, 39
	s_and_b64 vcc, exec, s[8:9]
	v_readlane_b32 s19, v251, 40
	s_mov_b64 s[12:13], s[44:45]
	s_cbranch_vccnz .LBB0_332
	v_readlane_b32 s12, v251, 13
	v_readlane_b32 s13, v251, 14
	s_andn2_b64 vcc, exec, s[12:13]
	s_mov_b64 s[18:19], -1
	s_cbranch_vccnz .LBB0_330
	s_load_dwordx2 s[12:13], s[10:11], 0x8
	s_mov_b64 s[18:19], 0

.LBB0_332:
	s_lshl_b64 s[18:19], s[18:19], 12
	s_waitcnt lgkmcnt(0)
	s_add_u32 s12, s12, s18
	s_addc_u32 s13, s13, s19
	v_lshl_add_u64 v[10:11], v[142:143], 2, s[12:13]
	global_load_dwordx4 v[90:93], v[10:11], off sc1
	global_load_dwordx4 v[54:57], v[10:11], off offset:1024 sc1
	global_load_dwordx4 v[30:33], v[10:11], off offset:2048 sc1
	s_nop 0
	global_load_dwordx4 v[10:13], v[10:11], off offset:3072 sc1
	v_readlane_b32 s18, v251, 43
	s_and_b64 vcc, exec, s[8:9]
	v_readlane_b32 s19, v251, 44
	s_mov_b64 s[12:13], s[44:45]
	s_cbranch_vccnz .LBB0_337
	v_readlane_b32 s12, v251, 15
	v_readlane_b32 s13, v251, 16
	s_andn2_b64 vcc, exec, s[12:13]
	s_mov_b64 s[18:19], -1
	s_cbranch_vccnz .LBB0_335
	s_load_dwordx2 s[12:13], s[10:11], 0x8
	s_mov_b64 s[18:19], 0

.LBB0_337:
	s_lshl_b64 s[18:19], s[18:19], 12
	s_waitcnt lgkmcnt(0)
	s_add_u32 s12, s12, s18
	s_addc_u32 s13, s13, s19
	v_lshl_add_u64 v[18:19], v[142:143], 2, s[12:13]
	global_load_dwordx4 v[98:101], v[18:19], off sc1
	global_load_dwordx4 v[66:69], v[18:19], off offset:1024 sc1
	global_load_dwordx4 v[46:49], v[18:19], off offset:2048 sc1
	s_nop 0
	global_load_dwordx4 v[18:21], v[18:19], off offset:3072 sc1
	v_readlane_b32 s18, v251, 47
	s_and_b64 vcc, exec, s[8:9]
	v_readlane_b32 s19, v251, 48
	s_mov_b64 s[12:13], s[44:45]
	s_cbranch_vccnz .LBB0_342
	v_readlane_b32 s12, v251, 17
	v_readlane_b32 s13, v251, 18
	s_andn2_b64 vcc, exec, s[12:13]
	s_mov_b64 s[18:19], -1
	s_cbranch_vccnz .LBB0_340
	s_load_dwordx2 s[12:13], s[10:11], 0x8
	s_mov_b64 s[18:19], 0

.LBB0_342:
	s_lshl_b64 s[18:19], s[18:19], 12
	s_waitcnt lgkmcnt(0)
	s_add_u32 s12, s12, s18
	s_addc_u32 s13, s13, s19
	v_lshl_add_u64 v[26:27], v[142:143], 2, s[12:13]
	global_load_dwordx4 v[110:113], v[26:27], off sc1
	global_load_dwordx4 v[82:85], v[26:27], off offset:1024 sc1
	global_load_dwordx4 v[58:61], v[26:27], off offset:2048 sc1
	s_nop 0
	global_load_dwordx4 v[26:29], v[26:27], off offset:3072 sc1
	v_readlane_b32 s18, v251, 51
	s_and_b64 vcc, exec, s[8:9]
	v_readlane_b32 s19, v251, 52
	s_mov_b64 s[12:13], s[44:45]
	s_cbranch_vccnz .LBB0_347
	v_readlane_b32 s12, v251, 19
	v_readlane_b32 s13, v251, 20
	s_andn2_b64 vcc, exec, s[12:13]
	s_mov_b64 s[18:19], -1
	s_cbranch_vccnz .LBB0_345
	s_load_dwordx2 s[12:13], s[10:11], 0x8
	s_mov_b64 s[18:19], 0

.LBB0_347:
	s_lshl_b64 s[18:19], s[18:19], 12
	s_waitcnt lgkmcnt(0)
	s_add_u32 s12, s12, s18
	s_addc_u32 s13, s13, s19
	v_lshl_add_u64 v[38:39], v[142:143], 2, s[12:13]
	global_load_dwordx4 v[114:117], v[38:39], off sc1
	global_load_dwordx4 v[94:97], v[38:39], off offset:1024 sc1
	global_load_dwordx4 v[70:73], v[38:39], off offset:2048 sc1
	s_nop 0
	global_load_dwordx4 v[38:41], v[38:39], off offset:3072 sc1
	v_readlane_b32 s12, v251, 55
	s_and_b64 vcc, exec, s[8:9]
	v_readlane_b32 s13, v251, 56
	s_mov_b64 s[8:9], s[44:45]
	s_cbranch_vccnz .LBB0_352
	v_readlane_b32 s8, v251, 21
	v_readlane_b32 s9, v251, 22
	s_andn2_b64 vcc, exec, s[8:9]
	s_mov_b64 s[12:13], -1
	s_cbranch_vccnz .LBB0_350
	s_load_dwordx2 s[8:9], s[10:11], 0x8
	s_mov_b64 s[12:13], 0

.LBB0_352:
	s_lshl_b64 s[12:13], s[12:13], 12
	s_waitcnt lgkmcnt(0)
	s_add_u32 s8, s8, s12
	s_addc_u32 s9, s9, s13
	v_lshl_add_u64 v[50:51], v[142:143], 2, s[8:9]
	global_load_dwordx4 v[122:125], v[50:51], off sc1
	global_load_dwordx4 v[106:109], v[50:51], off offset:1024 sc1
	global_load_dwordx4 v[86:89], v[50:51], off offset:2048 sc1
	s_nop 0
	global_load_dwordx4 v[50:53], v[50:51], off offset:3072 sc1
	v_readlane_b32 s8, v254, 55
	v_readlane_b32 s9, v254, 56
	s_andn2_b64 vcc, exec, s[8:9]
	s_mov_b64 s[12:13], -1
	s_cbranch_vccnz .LBB0_354
	v_readlane_b32 s8, v251, 23
	v_readlane_b32 s9, v251, 24
	s_add_u32 s8, s44, s8
	s_addc_u32 s9, s45, s9
	s_mov_b64 s[12:13], 0

.LBB0_359:
	s_waitcnt vmcnt(0)
	v_pk_mul_f32 v[138:139], v[64:65], v[64:65]
	v_pk_mul_f32 v[140:141], v[62:63], v[62:63]
	v_mul_f32_e32 v8, v0, v0
	v_pk_mov_b32 v[144:145], v[140:141], v[138:139] op_sel:[1,0]
	v_mov_b32_e32 v141, v139
	v_pk_add_f32 v[138:139], v[144:145], v[140:141]
	v_pk_mul_f32 v[140:141], v[36:37], v[36:37]
	v_pk_mul_f32 v[144:145], v[34:35], v[34:35]
	v_pk_add_f32 v[138:139], v[138:139], v[138:139] op_sel:[0,1] op_sel_hi:[1,0]
	v_pk_mov_b32 v[146:147], v[144:145], v[140:141] op_sel:[1,0]
	v_mov_b32_e32 v145, v141
	v_pk_add_f32 v[140:141], v[146:147], v[144:145]
	v_mul_f32_e32 v144, v1, v1
	v_pk_add_f32 v[140:141], v[140:141], v[140:141] op_sel:[0,1] op_sel_hi:[1,0]
	v_mov_b32_e32 v139, v8
	v_mov_b32_e32 v141, v144
	v_mul_f32_e32 v8, v15, v15
	v_mul_f32_e32 v145, v2, v2
	v_pk_add_f32 v[138:139], v[138:139], v[140:141]
	v_pk_fma_f32 v[140:141], v[14:15], v[14:15], v[8:9] op_sel_hi:[1,1,0]
	v_mul_f32_e32 v8, v17, v17
	v_mul_f32_e32 v146, v3, v3
	v_mov_b32_e32 v141, v145
	v_pk_fma_f32 v[144:145], v[16:17], v[16:17], v[8:9] op_sel_hi:[1,1,0]
	v_xor_b32_e32 v137, 4, v142
	v_mov_b32_e32 v145, v146
	v_pk_add_f32 v[140:141], v[140:141], v[144:145]
	v_xor_b32_e32 v136, 8, v142
	v_pk_add_f32 v[138:139], v[138:139], v[140:141]
	v_xor_b32_e32 v135, 16, v142
	v_add_f32_e32 v8, v138, v139
	ds_bpermute_b32 v138, v137, v8
	v_xor_b32_e32 v134, 32, v142
	v_xor_b32_e32 v133, 64, v142
	v_xor_b32_e32 v132, 0x80, v142
	s_mov_b32 s10, 0xf800000
	s_waitcnt lgkmcnt(0)
	v_add_f32_e32 v8, v8, v138
	ds_bpermute_b32 v138, v136, v8
	v_lshlrev_b64 v[130:131], 2, v[142:143]
	v_lshl_add_u64 v[74:75], s[8:9], 0, v[130:131]
	global_load_dwordx4 v[126:129], v[74:75], off sc1
	global_load_dwordx4 v[118:121], v[74:75], off offset:1024 sc1
	global_load_dwordx4 v[102:105], v[74:75], off offset:2048 sc1
	s_nop 0
	global_load_dwordx4 v[74:77], v[74:75], off offset:3072 sc1
	s_mov_b32 s92, 0xf800000
	s_waitcnt lgkmcnt(0)
	v_add_f32_e32 v8, v8, v138
	ds_bpermute_b32 v138, v135, v8
	s_waitcnt lgkmcnt(0)
	v_add_f32_e32 v8, v8, v138
	ds_bpermute_b32 v138, v134, v8
	s_waitcnt lgkmcnt(0)
	v_add_f32_e32 v8, v8, v138
	ds_bpermute_b32 v138, v133, v8
	s_waitcnt lgkmcnt(0)
	v_add_f32_e32 v8, v8, v138
	ds_bpermute_b32 v138, v132, v8
	s_waitcnt lgkmcnt(0)
	v_add_f32_e32 v8, v8, v138
	v_fmamk_f32 v8, v8, 0x3a800000, v236
	v_cmp_gt_f32_e32 vcc, s10, v8
	v_mul_f32_e32 v138, 0x4f800000, v8
	s_nop 0
	v_cndmask_b32_e32 v8, v8, v138, vcc
	v_sqrt_f32_e32 v138, v8
	s_nop 0
	v_add_u32_e32 v139, -1, v138
	v_fma_f32 v140, -v139, v138, v8
	v_cmp_ge_f32_e64 s[8:9], 0, v140
	v_add_u32_e32 v140, 1, v138
	s_nop 0
	v_cndmask_b32_e64 v139, v138, v139, s[8:9]
	v_fma_f32 v138, -v140, v138, v8
	v_cmp_lt_f32_e64 s[8:9], 0, v138
	s_nop 1
	v_cndmask_b32_e64 v138, v139, v140, s[8:9]
	v_mul_f32_e32 v139, 0x37800000, v138
	v_cndmask_b32_e32 v138, v138, v139, vcc
	v_cmp_class_f32_e32 vcc, v8, v237
	s_nop 1
	v_cndmask_b32_e32 v8, v138, v8, vcc
	v_div_scale_f32 v138, s[8:9], v8, v8, 1.0
	v_rcp_f32_e32 v139, v138
	s_nop 0
	v_fma_f32 v140, -v138, v139, 1.0
	v_fmac_f32_e32 v139, v140, v139
	v_div_scale_f32 v140, vcc, 1.0, v8, 1.0
	v_mul_f32_e32 v141, v140, v139
	v_fma_f32 v144, -v138, v141, v140
	v_fmac_f32_e32 v141, v144, v139
	v_fma_f32 v138, -v138, v141, v140
	v_div_fmas_f32 v138, v138, v139, v141
	v_div_fixup_f32 v8, v138, v8, 1.0
	v_pk_mul_f32 v[138:139], v[80:81], v[80:81]
	v_pk_mul_f32 v[140:141], v[78:79], v[78:79]
	v_pk_mul_f32 v[62:63], v[62:63], v[8:9] op_sel_hi:[1,0]
	v_pk_mov_b32 v[144:145], v[140:141], v[138:139] op_sel:[1,0]
	v_mov_b32_e32 v141, v139
	v_pk_add_f32 v[138:139], v[144:145], v[140:141]
	v_pk_mul_f32 v[140:141], v[44:45], v[44:45]
	v_pk_mul_f32 v[144:145], v[42:43], v[42:43]
	v_pk_add_f32 v[138:139], v[138:139], v[138:139] op_sel:[0,1] op_sel_hi:[1,0]
	v_pk_mov_b32 v[146:147], v[144:145], v[140:141] op_sel:[1,0]
	v_mov_b32_e32 v145, v141
	v_pk_add_f32 v[140:141], v[146:147], v[144:145]
	v_mul_f32_e32 v144, v4, v4
	v_mul_f32_e32 v145, v5, v5
	v_pk_add_f32 v[140:141], v[140:141], v[140:141] op_sel:[0,1] op_sel_hi:[1,0]
	v_mov_b32_e32 v139, v144
	v_mov_b32_e32 v141, v145
	v_pk_add_f32 v[138:139], v[138:139], v[140:141]
	v_mul_f32_e32 v140, v23, v23
	v_mul_f32_e32 v144, v25, v25
	v_mul_f32_e32 v146, v6, v6
	v_mul_f32_e32 v147, v7, v7
	v_pk_fma_f32 v[140:141], v[22:23], v[22:23], v[140:141] op_sel_hi:[1,1,0]
	v_pk_fma_f32 v[144:145], v[24:25], v[24:25], v[144:145] op_sel_hi:[1,1,0]
	v_mov_b32_e32 v141, v146
	v_mov_b32_e32 v145, v147
	v_pk_add_f32 v[140:141], v[140:141], v[144:145]
	v_pk_mul_f32 v[64:65], v[64:65], v[8:9] op_sel_hi:[1,0]
	v_pk_add_f32 v[138:139], v[138:139], v[140:141]
	v_pk_mul_f32 v[34:35], v[34:35], v[8:9] op_sel_hi:[1,0]
	v_add_f32_e32 v138, v138, v139
	ds_bpermute_b32 v139, v137, v138
	v_pk_mul_f32 v[36:37], v[36:37], v[8:9] op_sel_hi:[1,0]
	v_pk_mul_f32 v[14:15], v[14:15], v[8:9] op_sel_hi:[1,0]
	v_pk_mul_f32 v[16:17], v[16:17], v[8:9] op_sel_hi:[1,0]
	v_pk_mul_f32 v[0:1], v[0:1], v[8:9] op_sel_hi:[1,0]
	s_waitcnt lgkmcnt(0)
	v_add_f32_e32 v138, v138, v139
	ds_bpermute_b32 v139, v136, v138
	v_pk_mul_f32 v[2:3], v[2:3], v[8:9] op_sel_hi:[1,0]
	s_waitcnt lgkmcnt(0)
	v_add_f32_e32 v138, v138, v139
	ds_bpermute_b32 v139, v135, v138
	s_waitcnt lgkmcnt(0)
	v_add_f32_e32 v138, v138, v139
	ds_bpermute_b32 v139, v134, v138
	s_waitcnt lgkmcnt(0)
	v_add_f32_e32 v138, v138, v139
	ds_bpermute_b32 v139, v133, v138
	s_waitcnt lgkmcnt(0)
	v_add_f32_e32 v138, v138, v139
	ds_bpermute_b32 v139, v132, v138
	s_waitcnt lgkmcnt(0)
	v_add_f32_e32 v138, v138, v139
	v_fmamk_f32 v138, v138, 0x3a800000, v236
	v_cmp_gt_f32_e32 vcc, s10, v138
	v_mul_f32_e32 v139, 0x4f800000, v138
	s_nop 0
	v_cndmask_b32_e32 v138, v138, v139, vcc
	v_sqrt_f32_e32 v139, v138
	s_nop 0
	v_add_u32_e32 v140, -1, v139
	v_fma_f32 v141, -v140, v139, v138
	v_cmp_ge_f32_e64 s[8:9], 0, v141
	v_add_u32_e32 v141, 1, v139
	s_nop 0
	v_cndmask_b32_e64 v140, v139, v140, s[8:9]
	v_fma_f32 v139, -v141, v139, v138
	v_cmp_lt_f32_e64 s[8:9], 0, v139
	s_nop 1
	v_cndmask_b32_e64 v139, v140, v141, s[8:9]
	v_mul_f32_e32 v140, 0x37800000, v139
	v_cndmask_b32_e32 v139, v139, v140, vcc
	v_cmp_class_f32_e32 vcc, v138, v237
	s_nop 1
	v_cndmask_b32_e32 v138, v139, v138, vcc
	v_div_scale_f32 v139, s[8:9], v138, v138, 1.0
	v_rcp_f32_e32 v140, v139
	s_nop 0
	v_fma_f32 v141, -v139, v140, 1.0
	v_fmac_f32_e32 v140, v141, v140
	v_div_scale_f32 v141, vcc, 1.0, v138, 1.0
	v_mul_f32_e32 v144, v141, v140
	v_fma_f32 v145, -v139, v144, v141
	v_fmac_f32_e32 v144, v145, v140
	v_fma_f32 v139, -v139, v144, v141
	v_div_fmas_f32 v139, v139, v140, v144
	v_div_fixup_f32 v144, v139, v138, 1.0
	v_pk_mul_f32 v[138:139], v[92:93], v[92:93]
	v_pk_mul_f32 v[140:141], v[90:91], v[90:91]
	v_mul_f32_e32 v145, v10, v10
	v_pk_mov_b32 v[146:147], v[140:141], v[138:139] op_sel:[1,0]
	v_mov_b32_e32 v141, v139
	v_pk_add_f32 v[138:139], v[146:147], v[140:141]
	v_pk_mul_f32 v[140:141], v[56:57], v[56:57]
	v_pk_mul_f32 v[146:147], v[54:55], v[54:55]
	v_pk_add_f32 v[138:139], v[138:139], v[138:139] op_sel:[0,1] op_sel_hi:[1,0]
	v_pk_mov_b32 v[148:149], v[146:147], v[140:141] op_sel:[1,0]
	v_mov_b32_e32 v147, v141
	v_pk_add_f32 v[140:141], v[148:149], v[146:147]
	v_mul_f32_e32 v146, v11, v11
	v_pk_add_f32 v[140:141], v[140:141], v[140:141] op_sel:[0,1] op_sel_hi:[1,0]
	v_mov_b32_e32 v139, v145
	v_mov_b32_e32 v141, v146
	v_pk_add_f32 v[138:139], v[138:139], v[140:141]
	v_mul_f32_e32 v140, v31, v31
	v_mul_f32_e32 v147, v12, v12
	v_pk_fma_f32 v[140:141], v[30:31], v[30:31], v[140:141] op_sel_hi:[1,1,0]
	v_mul_f32_e32 v146, v33, v33
	v_mul_f32_e32 v148, v13, v13
	v_mov_b32_e32 v141, v147
	v_pk_fma_f32 v[146:147], v[32:33], v[32:33], v[146:147] op_sel_hi:[1,1,0]
	s_nop 0
	v_mov_b32_e32 v147, v148
	v_pk_add_f32 v[140:141], v[140:141], v[146:147]
	v_mul_f32_e32 v147, v19, v19
	v_pk_add_f32 v[138:139], v[138:139], v[140:141]
	s_nop 0
	v_add_f32_e32 v138, v138, v139
	ds_bpermute_b32 v139, v137, v138
	s_waitcnt lgkmcnt(0)
	v_add_f32_e32 v138, v138, v139
	ds_bpermute_b32 v139, v136, v138
	s_waitcnt lgkmcnt(0)
	v_add_f32_e32 v138, v138, v139
	ds_bpermute_b32 v139, v135, v138
	s_waitcnt lgkmcnt(0)
	v_add_f32_e32 v138, v138, v139
	ds_bpermute_b32 v139, v134, v138
	s_waitcnt lgkmcnt(0)
	v_add_f32_e32 v138, v138, v139
	ds_bpermute_b32 v139, v133, v138
	s_waitcnt lgkmcnt(0)
	v_add_f32_e32 v138, v138, v139
	ds_bpermute_b32 v139, v132, v138
	s_waitcnt lgkmcnt(0)
	v_add_f32_e32 v138, v138, v139
	v_fmamk_f32 v138, v138, 0x3a800000, v236
	v_cmp_gt_f32_e32 vcc, s10, v138
	v_mul_f32_e32 v139, 0x4f800000, v138
	s_nop 0
	v_cndmask_b32_e32 v138, v138, v139, vcc
	v_sqrt_f32_e32 v139, v138
	s_nop 0
	v_add_u32_e32 v140, -1, v139
	v_fma_f32 v141, -v140, v139, v138
	v_cmp_ge_f32_e64 s[8:9], 0, v141
	v_add_u32_e32 v141, 1, v139
	s_nop 0
	v_cndmask_b32_e64 v140, v139, v140, s[8:9]
	v_fma_f32 v139, -v141, v139, v138
	v_cmp_lt_f32_e64 s[8:9], 0, v139
	s_nop 1
	v_cndmask_b32_e64 v139, v140, v141, s[8:9]
	v_mul_f32_e32 v140, 0x37800000, v139
	v_cndmask_b32_e32 v139, v139, v140, vcc
	v_cmp_class_f32_e32 vcc, v138, v237
	s_nop 1
	v_cndmask_b32_e32 v138, v139, v138, vcc
	v_div_scale_f32 v139, s[8:9], v138, v138, 1.0
	v_rcp_f32_e32 v140, v139
	s_nop 0
	v_fma_f32 v141, -v139, v140, 1.0
	v_fmac_f32_e32 v140, v141, v140
	v_div_scale_f32 v141, vcc, 1.0, v138, 1.0
	v_mul_f32_e32 v145, v141, v140
	v_fma_f32 v146, -v139, v145, v141
	v_fmac_f32_e32 v145, v146, v140
	v_fma_f32 v139, -v139, v145, v141
	v_div_fmas_f32 v139, v139, v140, v145
	v_div_fixup_f32 v146, v139, v138, 1.0
	v_pk_mul_f32 v[138:139], v[100:101], v[100:101]
	v_pk_mul_f32 v[140:141], v[98:99], v[98:99]
	v_mul_f32_e32 v145, v18, v18
	v_pk_mov_b32 v[148:149], v[140:141], v[138:139] op_sel:[1,0]
	v_mov_b32_e32 v141, v139
	v_pk_add_f32 v[138:139], v[148:149], v[140:141]
	v_pk_mul_f32 v[140:141], v[68:69], v[68:69]
	v_pk_mul_f32 v[148:149], v[66:67], v[66:67]
	v_pk_add_f32 v[138:139], v[138:139], v[138:139] op_sel:[0,1] op_sel_hi:[1,0]
	v_pk_mov_b32 v[150:151], v[148:149], v[140:141] op_sel:[1,0]
	v_mov_b32_e32 v149, v141
	v_pk_add_f32 v[140:141], v[150:151], v[148:149]
	v_mov_b32_e32 v139, v145
	v_pk_add_f32 v[140:141], v[140:141], v[140:141] op_sel:[0,1] op_sel_hi:[1,0]
	v_mul_f32_e32 v148, v20, v20
	v_mov_b32_e32 v141, v147
	v_pk_add_f32 v[138:139], v[138:139], v[140:141]
	v_mul_f32_e32 v140, v47, v47
	v_pk_fma_f32 v[140:141], v[46:47], v[46:47], v[140:141] op_sel_hi:[1,1,0]
	v_mul_f32_e32 v150, v21, v21
	v_mov_b32_e32 v141, v148
	v_mul_f32_e32 v148, v49, v49
	v_pk_fma_f32 v[148:149], v[48:49], v[48:49], v[148:149] op_sel_hi:[1,1,0]
	s_nop 0
	v_mov_b32_e32 v149, v150
	v_pk_add_f32 v[140:141], v[140:141], v[148:149]
	v_mul_f32_e32 v149, v28, v28
	v_pk_add_f32 v[138:139], v[138:139], v[140:141]
	s_nop 0
	v_add_f32_e32 v138, v138, v139
	ds_bpermute_b32 v139, v137, v138
	s_waitcnt lgkmcnt(0)
	v_add_f32_e32 v138, v138, v139
	ds_bpermute_b32 v139, v136, v138
	s_waitcnt lgkmcnt(0)
	v_add_f32_e32 v138, v138, v139
	ds_bpermute_b32 v139, v135, v138
	s_waitcnt lgkmcnt(0)
	v_add_f32_e32 v138, v138, v139
	ds_bpermute_b32 v139, v134, v138
	s_waitcnt lgkmcnt(0)
	v_add_f32_e32 v138, v138, v139
	ds_bpermute_b32 v139, v133, v138
	s_waitcnt lgkmcnt(0)
	v_add_f32_e32 v138, v138, v139
	ds_bpermute_b32 v139, v132, v138
	s_waitcnt lgkmcnt(0)
	v_add_f32_e32 v138, v138, v139
	v_fmamk_f32 v138, v138, 0x3a800000, v236
	v_cmp_gt_f32_e32 vcc, s10, v138
	v_mul_f32_e32 v139, 0x4f800000, v138
	s_nop 0
	v_cndmask_b32_e32 v138, v138, v139, vcc
	v_sqrt_f32_e32 v139, v138
	s_nop 0
	v_add_u32_e32 v140, -1, v139
	v_fma_f32 v141, -v140, v139, v138
	v_cmp_ge_f32_e64 s[8:9], 0, v141
	v_add_u32_e32 v141, 1, v139
	s_nop 0
	v_cndmask_b32_e64 v140, v139, v140, s[8:9]
	v_fma_f32 v139, -v141, v139, v138
	v_cmp_lt_f32_e64 s[8:9], 0, v139
	s_nop 1
	v_cndmask_b32_e64 v139, v140, v141, s[8:9]
	v_mul_f32_e32 v140, 0x37800000, v139
	v_cndmask_b32_e32 v139, v139, v140, vcc
	v_cmp_class_f32_e32 vcc, v138, v237
	s_nop 1
	v_cndmask_b32_e32 v138, v139, v138, vcc
	v_div_scale_f32 v139, s[8:9], v138, v138, 1.0
	v_rcp_f32_e32 v140, v139
	s_nop 0
	v_fma_f32 v141, -v139, v140, 1.0
	v_fmac_f32_e32 v140, v141, v140
	v_div_scale_f32 v141, vcc, 1.0, v138, 1.0
	v_mul_f32_e32 v145, v141, v140
	v_fma_f32 v147, -v139, v145, v141
	v_fmac_f32_e32 v145, v147, v140
	v_fma_f32 v139, -v139, v145, v141
	v_div_fmas_f32 v139, v139, v140, v145
	v_div_fixup_f32 v148, v139, v138, 1.0
	v_pk_mul_f32 v[138:139], v[112:113], v[112:113]
	v_pk_mul_f32 v[140:141], v[110:111], v[110:111]
	v_mul_f32_e32 v145, v26, v26
	v_pk_mov_b32 v[150:151], v[140:141], v[138:139] op_sel:[1,0]
	v_mov_b32_e32 v141, v139
	v_pk_add_f32 v[138:139], v[150:151], v[140:141]
	v_pk_mul_f32 v[140:141], v[84:85], v[84:85]
	v_pk_mul_f32 v[150:151], v[82:83], v[82:83]
	v_mul_f32_e32 v147, v27, v27
	v_pk_mov_b32 v[152:153], v[150:151], v[140:141] op_sel:[1,0]
	v_mov_b32_e32 v151, v141
	v_pk_add_f32 v[140:141], v[152:153], v[150:151]
	v_pk_add_f32 v[138:139], v[138:139], v[138:139] op_sel:[0,1] op_sel_hi:[1,0]
	v_pk_add_f32 v[140:141], v[140:141], v[140:141] op_sel:[0,1] op_sel_hi:[1,0]
	v_mov_b32_e32 v139, v145
	v_mov_b32_e32 v141, v147
	v_pk_add_f32 v[138:139], v[138:139], v[140:141]
	v_mul_f32_e32 v140, v59, v59
	v_mul_f32_e32 v150, v61, v61
	v_mul_f32_e32 v152, v29, v29
	v_pk_fma_f32 v[140:141], v[58:59], v[58:59], v[140:141] op_sel_hi:[1,1,0]
	v_pk_fma_f32 v[150:151], v[60:61], v[60:61], v[150:151] op_sel_hi:[1,1,0]
	v_mov_b32_e32 v141, v149
	v_mov_b32_e32 v151, v152
	v_pk_add_f32 v[140:141], v[140:141], v[150:151]
	v_mul_f32_e32 v149, v40, v40
	v_pk_add_f32 v[138:139], v[138:139], v[140:141]
	v_mul_f32_e32 v151, v41, v41
	v_add_f32_e32 v138, v138, v139
	ds_bpermute_b32 v139, v137, v138
	s_waitcnt lgkmcnt(0)
	v_add_f32_e32 v138, v138, v139
	ds_bpermute_b32 v139, v136, v138
	s_waitcnt lgkmcnt(0)
	v_add_f32_e32 v138, v138, v139
	ds_bpermute_b32 v139, v135, v138
	s_waitcnt lgkmcnt(0)
	v_add_f32_e32 v138, v138, v139
	ds_bpermute_b32 v139, v134, v138
	s_waitcnt lgkmcnt(0)
	v_add_f32_e32 v138, v138, v139
	ds_bpermute_b32 v139, v133, v138
	s_waitcnt lgkmcnt(0)
	v_add_f32_e32 v138, v138, v139
	ds_bpermute_b32 v139, v132, v138
	s_waitcnt lgkmcnt(0)
	v_add_f32_e32 v138, v138, v139
	v_fmamk_f32 v138, v138, 0x3a800000, v236
	v_cmp_gt_f32_e32 vcc, s10, v138
	v_mul_f32_e32 v139, 0x4f800000, v138
	s_nop 0
	v_cndmask_b32_e32 v138, v138, v139, vcc
	v_sqrt_f32_e32 v139, v138
	s_nop 0
	v_add_u32_e32 v140, -1, v139
	v_fma_f32 v141, -v140, v139, v138
	v_cmp_ge_f32_e64 s[8:9], 0, v141
	v_add_u32_e32 v141, 1, v139
	s_nop 0
	v_cndmask_b32_e64 v140, v139, v140, s[8:9]
	v_fma_f32 v139, -v141, v139, v138
	v_cmp_lt_f32_e64 s[8:9], 0, v139
	s_nop 1
	v_cndmask_b32_e64 v139, v140, v141, s[8:9]
	v_mul_f32_e32 v140, 0x37800000, v139
	v_cndmask_b32_e32 v139, v139, v140, vcc
	v_cmp_class_f32_e32 vcc, v138, v237
	s_nop 1
	v_cndmask_b32_e32 v138, v139, v138, vcc
	v_div_scale_f32 v139, s[8:9], v138, v138, 1.0
	v_rcp_f32_e32 v140, v139
	s_nop 0
	v_fma_f32 v141, -v139, v140, 1.0
	v_fmac_f32_e32 v140, v141, v140
	v_div_scale_f32 v141, vcc, 1.0, v138, 1.0
	v_mul_f32_e32 v145, v141, v140
	v_fma_f32 v147, -v139, v145, v141
	v_fmac_f32_e32 v145, v147, v140
	v_fma_f32 v139, -v139, v145, v141
	v_div_fmas_f32 v139, v139, v140, v145
	v_div_fixup_f32 v150, v139, v138, 1.0
	v_pk_mul_f32 v[138:139], v[116:117], v[116:117]
	v_pk_mul_f32 v[140:141], v[114:115], v[114:115]
	v_mul_f32_e32 v145, v38, v38
	v_pk_mov_b32 v[152:153], v[140:141], v[138:139] op_sel:[1,0]
	v_mov_b32_e32 v141, v139
	v_pk_add_f32 v[138:139], v[152:153], v[140:141]
	v_pk_mul_f32 v[140:141], v[96:97], v[96:97]
	v_pk_mul_f32 v[152:153], v[94:95], v[94:95]
	v_mul_f32_e32 v147, v39, v39
	v_pk_mov_b32 v[154:155], v[152:153], v[140:141] op_sel:[1,0]
	v_mov_b32_e32 v153, v141
	v_pk_add_f32 v[140:141], v[154:155], v[152:153]
	v_pk_add_f32 v[138:139], v[138:139], v[138:139] op_sel:[0,1] op_sel_hi:[1,0]
	v_pk_add_f32 v[140:141], v[140:141], v[140:141] op_sel:[0,1] op_sel_hi:[1,0]
	v_mov_b32_e32 v139, v145
	v_mov_b32_e32 v141, v147
	v_pk_add_f32 v[138:139], v[138:139], v[140:141]
	v_mul_f32_e32 v140, v71, v71
	v_mul_f32_e32 v152, v73, v73
	v_pk_fma_f32 v[140:141], v[70:71], v[70:71], v[140:141] op_sel_hi:[1,1,0]
	v_pk_fma_f32 v[152:153], v[72:73], v[72:73], v[152:153] op_sel_hi:[1,1,0]
	v_mov_b32_e32 v141, v149
	v_mov_b32_e32 v153, v151
	v_pk_add_f32 v[140:141], v[140:141], v[152:153]
	v_mul_f32_e32 v149, v52, v52
	v_pk_add_f32 v[138:139], v[138:139], v[140:141]
	v_mul_f32_e32 v151, v53, v53
	v_add_f32_e32 v138, v138, v139
	ds_bpermute_b32 v139, v137, v138
	s_waitcnt lgkmcnt(0)
	v_add_f32_e32 v138, v138, v139
	ds_bpermute_b32 v139, v136, v138
	s_waitcnt lgkmcnt(0)
	v_add_f32_e32 v138, v138, v139
	ds_bpermute_b32 v139, v135, v138
	s_waitcnt lgkmcnt(0)
	v_add_f32_e32 v138, v138, v139
	ds_bpermute_b32 v139, v134, v138
	s_waitcnt lgkmcnt(0)
	v_add_f32_e32 v138, v138, v139
	ds_bpermute_b32 v139, v133, v138
	s_waitcnt lgkmcnt(0)
	v_add_f32_e32 v138, v138, v139
	ds_bpermute_b32 v139, v132, v138
	s_waitcnt lgkmcnt(0)
	v_add_f32_e32 v138, v138, v139
	v_fmamk_f32 v138, v138, 0x3a800000, v236
	v_cmp_gt_f32_e32 vcc, s10, v138
	v_mul_f32_e32 v139, 0x4f800000, v138
	s_nop 0
	v_cndmask_b32_e32 v138, v138, v139, vcc
	v_sqrt_f32_e32 v139, v138
	s_nop 0
	v_add_u32_e32 v140, -1, v139
	v_fma_f32 v141, -v140, v139, v138
	v_cmp_ge_f32_e64 s[8:9], 0, v141
	v_add_u32_e32 v141, 1, v139
	s_nop 0
	v_cndmask_b32_e64 v140, v139, v140, s[8:9]
	v_fma_f32 v139, -v141, v139, v138
	v_cmp_lt_f32_e64 s[8:9], 0, v139
	s_nop 1
	v_cndmask_b32_e64 v139, v140, v141, s[8:9]
	v_mul_f32_e32 v140, 0x37800000, v139
	v_cndmask_b32_e32 v139, v139, v140, vcc
	v_cmp_class_f32_e32 vcc, v138, v237
	s_nop 1
	v_cndmask_b32_e32 v138, v139, v138, vcc
	v_div_scale_f32 v139, s[8:9], v138, v138, 1.0
	v_rcp_f32_e32 v140, v139
	s_nop 0
	v_fma_f32 v141, -v139, v140, 1.0
	v_fmac_f32_e32 v140, v141, v140
	v_div_scale_f32 v141, vcc, 1.0, v138, 1.0
	v_mul_f32_e32 v145, v141, v140
	v_fma_f32 v147, -v139, v145, v141
	v_fmac_f32_e32 v145, v147, v140
	v_fma_f32 v139, -v139, v145, v141
	v_div_fmas_f32 v139, v139, v140, v145
	v_div_fixup_f32 v152, v139, v138, 1.0
	v_pk_mul_f32 v[138:139], v[124:125], v[124:125]
	v_pk_mul_f32 v[140:141], v[122:123], v[122:123]
	v_mul_f32_e32 v145, v50, v50
	v_pk_mov_b32 v[154:155], v[140:141], v[138:139] op_sel:[1,0]
	v_mov_b32_e32 v141, v139
	v_pk_add_f32 v[138:139], v[154:155], v[140:141]
	v_pk_mul_f32 v[140:141], v[108:109], v[108:109]
	v_pk_mul_f32 v[154:155], v[106:107], v[106:107]
	v_mul_f32_e32 v147, v51, v51
	v_pk_mov_b32 v[156:157], v[154:155], v[140:141] op_sel:[1,0]
	v_mov_b32_e32 v155, v141
	v_pk_add_f32 v[140:141], v[156:157], v[154:155]
	v_pk_add_f32 v[138:139], v[138:139], v[138:139] op_sel:[0,1] op_sel_hi:[1,0]
	v_pk_add_f32 v[140:141], v[140:141], v[140:141] op_sel:[0,1] op_sel_hi:[1,0]
	v_mov_b32_e32 v139, v145
	v_mov_b32_e32 v141, v147
	v_pk_add_f32 v[138:139], v[138:139], v[140:141]
	v_mul_f32_e32 v140, v87, v87
	v_mul_f32_e32 v154, v89, v89
	v_pk_fma_f32 v[140:141], v[86:87], v[86:87], v[140:141] op_sel_hi:[1,1,0]
	v_pk_fma_f32 v[154:155], v[88:89], v[88:89], v[154:155] op_sel_hi:[1,1,0]
	v_mov_b32_e32 v141, v149
	v_mov_b32_e32 v155, v151
	v_pk_add_f32 v[140:141], v[140:141], v[154:155]
	s_waitcnt vmcnt(0)
	v_mul_f32_e32 v149, v76, v76
	v_pk_add_f32 v[138:139], v[138:139], v[140:141]
	v_mul_f32_e32 v151, v77, v77
	v_add_f32_e32 v138, v138, v139
	ds_bpermute_b32 v139, v137, v138
	s_waitcnt lgkmcnt(0)
	v_add_f32_e32 v138, v138, v139
	ds_bpermute_b32 v139, v136, v138
	s_waitcnt lgkmcnt(0)
	v_add_f32_e32 v138, v138, v139
	ds_bpermute_b32 v139, v135, v138
	s_waitcnt lgkmcnt(0)
	v_add_f32_e32 v138, v138, v139
	ds_bpermute_b32 v139, v134, v138
	s_waitcnt lgkmcnt(0)
	v_add_f32_e32 v138, v138, v139
	ds_bpermute_b32 v139, v133, v138
	s_waitcnt lgkmcnt(0)
	v_add_f32_e32 v138, v138, v139
	ds_bpermute_b32 v139, v132, v138
	s_waitcnt lgkmcnt(0)
	v_add_f32_e32 v138, v138, v139
	v_fmamk_f32 v138, v138, 0x3a800000, v236
	v_cmp_gt_f32_e32 vcc, s10, v138
	v_mul_f32_e32 v139, 0x4f800000, v138
	s_nop 0
	v_cndmask_b32_e32 v138, v138, v139, vcc
	v_sqrt_f32_e32 v139, v138
	s_nop 0
	v_add_u32_e32 v140, -1, v139
	v_fma_f32 v141, -v140, v139, v138
	v_cmp_ge_f32_e64 s[8:9], 0, v141
	v_add_u32_e32 v141, 1, v139
	s_nop 0
	v_cndmask_b32_e64 v140, v139, v140, s[8:9]
	v_fma_f32 v139, -v141, v139, v138
	v_cmp_lt_f32_e64 s[8:9], 0, v139
	s_nop 1
	v_cndmask_b32_e64 v139, v140, v141, s[8:9]
	v_mul_f32_e32 v140, 0x37800000, v139
	v_cndmask_b32_e32 v139, v139, v140, vcc
	v_cmp_class_f32_e32 vcc, v138, v237
	s_nop 1
	v_cndmask_b32_e32 v138, v139, v138, vcc
	v_div_scale_f32 v139, s[8:9], v138, v138, 1.0
	v_rcp_f32_e32 v140, v139
	s_nop 0
	v_fma_f32 v141, -v139, v140, 1.0
	v_fmac_f32_e32 v140, v141, v140
	v_div_scale_f32 v141, vcc, 1.0, v138, 1.0
	v_mul_f32_e32 v145, v141, v140
	v_fma_f32 v147, -v139, v145, v141
	v_fmac_f32_e32 v145, v147, v140
	v_fma_f32 v139, -v139, v145, v141
	v_div_fmas_f32 v139, v139, v140, v145
	v_div_fixup_f32 v154, v139, v138, 1.0
	v_pk_mul_f32 v[138:139], v[128:129], v[128:129]
	v_pk_mul_f32 v[140:141], v[126:127], v[126:127]
	v_mul_f32_e32 v145, v74, v74
	v_pk_mov_b32 v[156:157], v[140:141], v[138:139] op_sel:[1,0]
	v_mov_b32_e32 v141, v139
	v_pk_add_f32 v[138:139], v[156:157], v[140:141]
	v_pk_mul_f32 v[140:141], v[120:121], v[120:121]
	v_pk_mul_f32 v[156:157], v[118:119], v[118:119]
	v_mul_f32_e32 v147, v75, v75
	v_pk_mov_b32 v[158:159], v[156:157], v[140:141] op_sel:[1,0]
	v_mov_b32_e32 v157, v141
	v_pk_add_f32 v[140:141], v[158:159], v[156:157]
	v_pk_add_f32 v[138:139], v[138:139], v[138:139] op_sel:[0,1] op_sel_hi:[1,0]
	v_pk_add_f32 v[140:141], v[140:141], v[140:141] op_sel:[0,1] op_sel_hi:[1,0]
	v_mov_b32_e32 v139, v145
	v_mov_b32_e32 v141, v147
	v_pk_add_f32 v[138:139], v[138:139], v[140:141]
	v_mul_f32_e32 v140, v103, v103
	v_mul_f32_e32 v156, v105, v105
	v_pk_fma_f32 v[140:141], v[102:103], v[102:103], v[140:141] op_sel_hi:[1,1,0]
	v_pk_fma_f32 v[156:157], v[104:105], v[104:105], v[156:157] op_sel_hi:[1,1,0]
	v_mov_b32_e32 v141, v149
	v_mov_b32_e32 v157, v151
	v_pk_add_f32 v[140:141], v[140:141], v[156:157]
	v_lshl_add_u64 v[158:159], s[16:17], 0, v[130:131]
	v_pk_add_f32 v[138:139], v[138:139], v[140:141]
	s_nop 0
	v_add_f32_e32 v138, v138, v139
	ds_bpermute_b32 v137, v137, v138
	s_waitcnt lgkmcnt(0)
	v_add_f32_e32 v137, v138, v137
	ds_bpermute_b32 v136, v136, v137
	s_waitcnt lgkmcnt(0)
	v_add_f32_e32 v136, v137, v136
	ds_bpermute_b32 v135, v135, v136
	s_waitcnt lgkmcnt(0)
	v_add_f32_e32 v135, v136, v135
	ds_bpermute_b32 v134, v134, v135
	s_waitcnt lgkmcnt(0)
	v_add_f32_e32 v134, v135, v134
	ds_bpermute_b32 v133, v133, v134
	s_waitcnt lgkmcnt(0)
	v_add_f32_e32 v133, v134, v133
	ds_bpermute_b32 v132, v132, v133
	s_waitcnt lgkmcnt(0)
	v_add_f32_e32 v132, v133, v132
	v_fmamk_f32 v132, v132, 0x3a800000, v236
	v_cmp_gt_f32_e32 vcc, s10, v132
	v_mul_f32_e32 v133, 0x4f800000, v132
	s_nop 0
	v_cndmask_b32_e32 v132, v132, v133, vcc
	v_sqrt_f32_e32 v133, v132
	s_nop 0
	v_add_u32_e32 v134, -1, v133
	v_fma_f32 v135, -v134, v133, v132
	v_cmp_ge_f32_e64 s[8:9], 0, v135
	v_add_u32_e32 v135, 1, v133
	s_nop 0
	v_cndmask_b32_e64 v134, v133, v134, s[8:9]
	v_fma_f32 v133, -v135, v133, v132
	v_cmp_lt_f32_e64 s[8:9], 0, v133
	s_nop 1
	v_cndmask_b32_e64 v133, v134, v135, s[8:9]
	v_mul_f32_e32 v134, 0x37800000, v133
	v_cndmask_b32_e32 v133, v133, v134, vcc
	v_cmp_class_f32_e32 vcc, v132, v237
	s_nop 1
	v_cndmask_b32_e32 v132, v133, v132, vcc
	v_div_scale_f32 v133, s[8:9], v132, v132, 1.0
	v_rcp_f32_e32 v134, v133
	v_readlane_b32 s8, v253, 54
	s_add_u32 s6, s6, s8
	v_readlane_b32 s8, v253, 53
	v_fma_f32 v135, -v133, v134, 1.0
	v_fmac_f32_e32 v134, v135, v134
	v_div_scale_f32 v135, vcc, 1.0, v132, 1.0
	v_mul_f32_e32 v136, v135, v134
	v_fma_f32 v137, -v133, v136, v135
	s_addc_u32 s7, s7, s8
	v_fmac_f32_e32 v136, v137, v134
	v_lshl_add_u64 v[162:163], s[6:7], 0, v[130:131]
	s_mov_b64 s[6:7], 0x1000
	v_fma_f32 v133, -v133, v136, v135
	v_lshl_add_u64 v[160:161], v[162:163], 0, s[6:7]
	s_movk_i32 s6, 0x1000
	v_div_fmas_f32 v133, v133, v134, v136
	v_add_co_u32_e32 v138, vcc, s6, v162
	global_load_dwordx4 v[134:137], v[158:159], off
	s_nop 0
	v_addc_co_u32_e32 v139, vcc, 0, v163, vcc
	global_load_dwordx4 v[138:141], v[138:139], off
	v_div_fixup_f32 v156, v133, v132, 1.0
	global_load_dwordx4 v[130:133], v[162:163], off
	v_readlane_b32 s6, v251, 33
	v_readlane_b32 s7, v251, 34
	s_waitcnt vmcnt(1)
	v_pk_add_f32 v[140:141], v[140:141], 1.0 op_sel_hi:[1,0]
	v_pk_add_f32 v[138:139], v[138:139], 1.0 op_sel_hi:[1,0]
	v_pk_mul_f32 v[136:137], v[136:137], v[140:141]
	v_pk_mul_f32 v[134:135], v[134:135], v[138:139]
	v_lshl_add_u64 v[138:139], v[142:143], 1, s[14:15]
	s_waitcnt vmcnt(0)
	v_pk_fma_f32 v[64:65], v[64:65], v[136:137], v[132:133]
	v_pk_fma_f32 v[62:63], v[62:63], v[134:135], v[130:131]
	v_cvt_pk_bf16_f32 v141, v64, v65
	v_cvt_pk_bf16_f32 v140, v62, v63
	v_lshl_add_u64 v[62:63], v[138:139], 0, s[6:7]
	v_pk_mul_f32 v[64:65], v[78:79], v[144:145] op_sel_hi:[1,0]
	v_pk_mul_f32 v[78:79], v[80:81], v[144:145] op_sel_hi:[1,0]
	v_readlane_b32 s6, v251, 37
	v_pk_fma_f32 v[78:79], v[78:79], v[136:137], v[132:133]
	v_pk_fma_f32 v[64:65], v[64:65], v[134:135], v[130:131]
	v_readlane_b32 s7, v251, 38
	v_cvt_pk_bf16_f32 v80, v64, v65
	v_cvt_pk_bf16_f32 v81, v78, v79
	v_lshl_add_u64 v[64:65], v[138:139], 0, s[6:7]
	global_store_dwordx2 v[64:65], v[80:81], off
	v_pk_mul_f32 v[78:79], v[90:91], v[146:147] op_sel_hi:[1,0]
	v_pk_mul_f32 v[80:81], v[92:93], v[146:147] op_sel_hi:[1,0]
	v_readlane_b32 s6, v251, 41
	v_pk_fma_f32 v[80:81], v[80:81], v[136:137], v[132:133]
	v_pk_fma_f32 v[78:79], v[78:79], v[134:135], v[130:131]
	v_readlane_b32 s7, v251, 42
	v_cvt_pk_bf16_f32 v90, v78, v79
	v_cvt_pk_bf16_f32 v91, v80, v81
	v_lshl_add_u64 v[78:79], v[138:139], 0, s[6:7]
	global_store_dwordx2 v[78:79], v[90:91], off
	v_pk_mul_f32 v[80:81], v[98:99], v[148:149] op_sel_hi:[1,0]
	v_pk_mul_f32 v[90:91], v[100:101], v[148:149] op_sel_hi:[1,0]
	v_readlane_b32 s6, v251, 45
	v_pk_fma_f32 v[90:91], v[90:91], v[136:137], v[132:133]
	v_pk_fma_f32 v[80:81], v[80:81], v[134:135], v[130:131]
	v_readlane_b32 s7, v251, 46
	v_cvt_pk_bf16_f32 v92, v80, v81
	v_cvt_pk_bf16_f32 v93, v90, v91
	v_lshl_add_u64 v[80:81], v[138:139], 0, s[6:7]
	global_store_dwordx2 v[80:81], v[92:93], off
	v_pk_mul_f32 v[90:91], v[110:111], v[150:151] op_sel_hi:[1,0]
	v_pk_mul_f32 v[92:93], v[112:113], v[150:151] op_sel_hi:[1,0]
	v_readlane_b32 s6, v251, 49
	v_pk_fma_f32 v[92:93], v[92:93], v[136:137], v[132:133]
	v_pk_fma_f32 v[90:91], v[90:91], v[134:135], v[130:131]
	v_readlane_b32 s7, v251, 50
	v_cvt_pk_bf16_f32 v98, v90, v91
	v_cvt_pk_bf16_f32 v99, v92, v93
	v_lshl_add_u64 v[90:91], v[138:139], 0, s[6:7]
	global_store_dwordx2 v[90:91], v[98:99], off
	v_pk_mul_f32 v[92:93], v[114:115], v[152:153] op_sel_hi:[1,0]
	v_pk_mul_f32 v[98:99], v[116:117], v[152:153] op_sel_hi:[1,0]
	v_readlane_b32 s6, v251, 53
	v_pk_fma_f32 v[98:99], v[98:99], v[136:137], v[132:133]
	v_pk_fma_f32 v[92:93], v[92:93], v[134:135], v[130:131]
	v_readlane_b32 s7, v251, 54
	v_cvt_pk_bf16_f32 v100, v92, v93
	v_cvt_pk_bf16_f32 v101, v98, v99
	v_lshl_add_u64 v[92:93], v[138:139], 0, s[6:7]
	global_store_dwordx2 v[92:93], v[100:101], off
	v_pk_mul_f32 v[98:99], v[122:123], v[154:155] op_sel_hi:[1,0]
	v_pk_mul_f32 v[100:101], v[124:125], v[154:155] op_sel_hi:[1,0]
	v_readlane_b32 s6, v251, 57
	v_pk_fma_f32 v[100:101], v[100:101], v[136:137], v[132:133]
	v_pk_fma_f32 v[98:99], v[98:99], v[134:135], v[130:131]
	v_readlane_b32 s7, v251, 58
	v_cvt_pk_bf16_f32 v110, v98, v99
	v_cvt_pk_bf16_f32 v111, v100, v101
	v_lshl_add_u64 v[98:99], v[138:139], 0, s[6:7]
	global_store_dwordx2 v[98:99], v[110:111], off
	v_pk_mul_f32 v[100:101], v[126:127], v[156:157] op_sel_hi:[1,0]
	v_pk_mul_f32 v[110:111], v[128:129], v[156:157] op_sel_hi:[1,0]
	v_pk_fma_f32 v[100:101], v[134:135], v[100:101], v[130:131]
	v_pk_fma_f32 v[110:111], v[136:137], v[110:111], v[132:133]
	s_lshl_b64 s[6:7], s[12:13], 11
	v_cvt_pk_bf16_f32 v112, v100, v101
	v_cvt_pk_bf16_f32 v113, v110, v111
	v_lshl_add_u64 v[100:101], v[138:139], 0, s[6:7]
	global_store_dwordx2 v[62:63], v[140:141], off
	global_store_dwordx2 v[100:101], v[112:113], off
	global_load_dwordx4 v[110:113], v[158:159], off offset:1024
	s_nop 0
	global_load_dwordx4 v[114:117], v[162:163], off offset:1024
	global_load_dwordx4 v[122:125], v[160:161], off offset:1024
	s_waitcnt vmcnt(0)
	v_pk_add_f32 v[124:125], v[124:125], 1.0 op_sel_hi:[1,0]
	v_pk_add_f32 v[122:123], v[122:123], 1.0 op_sel_hi:[1,0]
	v_pk_mul_f32 v[112:113], v[112:113], v[124:125]
	v_pk_mul_f32 v[110:111], v[110:111], v[122:123]
	v_pk_fma_f32 v[36:37], v[36:37], v[112:113], v[116:117]
	v_pk_fma_f32 v[34:35], v[34:35], v[110:111], v[114:115]
	s_nop 0
	v_cvt_pk_bf16_f32 v34, v34, v35
	v_cvt_pk_bf16_f32 v35, v36, v37
	global_store_dwordx2 v[62:63], v[34:35], off offset:512
	v_pk_mul_f32 v[34:35], v[42:43], v[144:145] op_sel_hi:[1,0]
	v_pk_mul_f32 v[36:37], v[44:45], v[144:145] op_sel_hi:[1,0]
	v_pk_fma_f32 v[34:35], v[34:35], v[110:111], v[114:115]
	v_pk_fma_f32 v[36:37], v[36:37], v[112:113], v[116:117]
	v_cvt_pk_bf16_f32 v34, v34, v35
	v_cvt_pk_bf16_f32 v35, v36, v37
	global_store_dwordx2 v[64:65], v[34:35], off offset:512
	v_pk_mul_f32 v[34:35], v[54:55], v[146:147] op_sel_hi:[1,0]
	v_pk_mul_f32 v[36:37], v[56:57], v[146:147] op_sel_hi:[1,0]
	v_pk_fma_f32 v[34:35], v[34:35], v[110:111], v[114:115]
	v_pk_fma_f32 v[36:37], v[36:37], v[112:113], v[116:117]
	v_cvt_pk_bf16_f32 v34, v34, v35
	v_cvt_pk_bf16_f32 v35, v36, v37
	global_store_dwordx2 v[78:79], v[34:35], off offset:512
	v_pk_mul_f32 v[34:35], v[66:67], v[148:149] op_sel_hi:[1,0]
	v_pk_mul_f32 v[36:37], v[68:69], v[148:149] op_sel_hi:[1,0]
	v_pk_fma_f32 v[34:35], v[34:35], v[110:111], v[114:115]
	v_pk_fma_f32 v[36:37], v[36:37], v[112:113], v[116:117]
	v_cvt_pk_bf16_f32 v34, v34, v35
	v_cvt_pk_bf16_f32 v35, v36, v37
	global_store_dwordx2 v[80:81], v[34:35], off offset:512
	v_pk_mul_f32 v[34:35], v[82:83], v[150:151] op_sel_hi:[1,0]
	v_pk_mul_f32 v[36:37], v[84:85], v[150:151] op_sel_hi:[1,0]
	v_pk_fma_f32 v[34:35], v[34:35], v[110:111], v[114:115]
	v_pk_fma_f32 v[36:37], v[36:37], v[112:113], v[116:117]
	v_cvt_pk_bf16_f32 v34, v34, v35
	v_cvt_pk_bf16_f32 v35, v36, v37
	global_store_dwordx2 v[90:91], v[34:35], off offset:512
	v_pk_mul_f32 v[34:35], v[94:95], v[152:153] op_sel_hi:[1,0]
	v_pk_mul_f32 v[36:37], v[96:97], v[152:153] op_sel_hi:[1,0]
	v_pk_fma_f32 v[34:35], v[34:35], v[110:111], v[114:115]
	v_pk_fma_f32 v[36:37], v[36:37], v[112:113], v[116:117]
	v_cvt_pk_bf16_f32 v34, v34, v35
	v_cvt_pk_bf16_f32 v35, v36, v37
	global_store_dwordx2 v[92:93], v[34:35], off offset:512
	v_pk_mul_f32 v[34:35], v[106:107], v[154:155] op_sel_hi:[1,0]
	v_pk_mul_f32 v[36:37], v[108:109], v[154:155] op_sel_hi:[1,0]
	v_pk_fma_f32 v[34:35], v[34:35], v[110:111], v[114:115]
	v_pk_fma_f32 v[36:37], v[36:37], v[112:113], v[116:117]
	v_cvt_pk_bf16_f32 v34, v34, v35
	v_cvt_pk_bf16_f32 v35, v36, v37
	global_store_dwordx2 v[98:99], v[34:35], off offset:512
	v_pk_mul_f32 v[34:35], v[118:119], v[156:157] op_sel_hi:[1,0]
	v_pk_mul_f32 v[36:37], v[120:121], v[156:157] op_sel_hi:[1,0]
	v_pk_fma_f32 v[34:35], v[34:35], v[110:111], v[114:115]
	v_pk_fma_f32 v[36:37], v[36:37], v[112:113], v[116:117]
	v_cvt_pk_bf16_f32 v34, v34, v35
	v_cvt_pk_bf16_f32 v35, v36, v37
	global_store_dwordx2 v[100:101], v[34:35], off offset:512
	global_load_dwordx4 v[34:37], v[158:159], off offset:2048
	s_nop 0
	global_load_dwordx4 v[42:45], v[162:163], off offset:2048
	global_load_dwordx4 v[54:57], v[160:161], off offset:2048
	s_waitcnt vmcnt(0)
	v_pk_add_f32 v[56:57], v[56:57], 1.0 op_sel_hi:[1,0]
	v_pk_add_f32 v[54:55], v[54:55], 1.0 op_sel_hi:[1,0]
	v_pk_mul_f32 v[36:37], v[36:37], v[56:57]
	v_pk_mul_f32 v[34:35], v[34:35], v[54:55]
	v_pk_fma_f32 v[16:17], v[16:17], v[36:37], v[44:45]
	v_pk_fma_f32 v[14:15], v[14:15], v[34:35], v[42:43]
	s_nop 0
	v_cvt_pk_bf16_f32 v14, v14, v15
	v_cvt_pk_bf16_f32 v15, v16, v17
	global_store_dwordx2 v[62:63], v[14:15], off offset:1024
	v_pk_mul_f32 v[14:15], v[22:23], v[144:145] op_sel_hi:[1,0]
	v_pk_mul_f32 v[16:17], v[24:25], v[144:145] op_sel_hi:[1,0]
	v_pk_fma_f32 v[14:15], v[14:15], v[34:35], v[42:43]
	v_pk_fma_f32 v[16:17], v[16:17], v[36:37], v[44:45]
	v_cvt_pk_bf16_f32 v14, v14, v15
	v_cvt_pk_bf16_f32 v15, v16, v17
	global_store_dwordx2 v[64:65], v[14:15], off offset:1024
	v_pk_mul_f32 v[14:15], v[30:31], v[146:147] op_sel_hi:[1,0]
	v_pk_mul_f32 v[16:17], v[32:33], v[146:147] op_sel_hi:[1,0]
	v_pk_fma_f32 v[14:15], v[14:15], v[34:35], v[42:43]
	v_pk_fma_f32 v[16:17], v[16:17], v[36:37], v[44:45]
	v_cvt_pk_bf16_f32 v14, v14, v15
	v_cvt_pk_bf16_f32 v15, v16, v17
	global_store_dwordx2 v[78:79], v[14:15], off offset:1024
	v_pk_mul_f32 v[14:15], v[46:47], v[148:149] op_sel_hi:[1,0]
	v_pk_mul_f32 v[16:17], v[48:49], v[148:149] op_sel_hi:[1,0]
	v_pk_fma_f32 v[14:15], v[14:15], v[34:35], v[42:43]
	v_pk_fma_f32 v[16:17], v[16:17], v[36:37], v[44:45]
	v_cvt_pk_bf16_f32 v14, v14, v15
	v_cvt_pk_bf16_f32 v15, v16, v17
	global_store_dwordx2 v[80:81], v[14:15], off offset:1024
	v_pk_mul_f32 v[14:15], v[58:59], v[150:151] op_sel_hi:[1,0]
	v_pk_mul_f32 v[16:17], v[60:61], v[150:151] op_sel_hi:[1,0]
	v_pk_fma_f32 v[14:15], v[14:15], v[34:35], v[42:43]
	v_pk_fma_f32 v[16:17], v[16:17], v[36:37], v[44:45]
	v_cvt_pk_bf16_f32 v14, v14, v15
	v_cvt_pk_bf16_f32 v15, v16, v17
	global_store_dwordx2 v[90:91], v[14:15], off offset:1024
	v_pk_mul_f32 v[14:15], v[70:71], v[152:153] op_sel_hi:[1,0]
	v_pk_mul_f32 v[16:17], v[72:73], v[152:153] op_sel_hi:[1,0]
	v_pk_fma_f32 v[14:15], v[14:15], v[34:35], v[42:43]
	v_pk_fma_f32 v[16:17], v[16:17], v[36:37], v[44:45]
	v_cvt_pk_bf16_f32 v14, v14, v15
	v_cvt_pk_bf16_f32 v15, v16, v17
	global_store_dwordx2 v[92:93], v[14:15], off offset:1024
	v_pk_mul_f32 v[14:15], v[86:87], v[154:155] op_sel_hi:[1,0]
	v_pk_mul_f32 v[16:17], v[88:89], v[154:155] op_sel_hi:[1,0]
	v_pk_fma_f32 v[14:15], v[14:15], v[34:35], v[42:43]
	v_pk_fma_f32 v[16:17], v[16:17], v[36:37], v[44:45]
	v_cvt_pk_bf16_f32 v14, v14, v15
	v_cvt_pk_bf16_f32 v15, v16, v17
	global_store_dwordx2 v[98:99], v[14:15], off offset:1024
	v_pk_mul_f32 v[14:15], v[102:103], v[156:157] op_sel_hi:[1,0]
	v_pk_mul_f32 v[16:17], v[104:105], v[156:157] op_sel_hi:[1,0]
	v_pk_fma_f32 v[14:15], v[14:15], v[34:35], v[42:43]
	v_pk_fma_f32 v[16:17], v[16:17], v[36:37], v[44:45]
	v_cvt_pk_bf16_f32 v14, v14, v15
	v_cvt_pk_bf16_f32 v15, v16, v17
	global_store_dwordx2 v[100:101], v[14:15], off offset:1024
	global_load_dwordx4 v[14:17], v[158:159], off offset:3072
	s_nop 0
	global_load_dwordx4 v[22:25], v[162:163], off offset:3072
	global_load_dwordx4 v[30:33], v[160:161], off offset:3072
	s_waitcnt vmcnt(0)
	v_pk_add_f32 v[32:33], v[32:33], 1.0 op_sel_hi:[1,0]
	v_pk_add_f32 v[30:31], v[30:31], 1.0 op_sel_hi:[1,0]
	v_pk_mul_f32 v[16:17], v[16:17], v[32:33]
	v_pk_mul_f32 v[14:15], v[14:15], v[30:31]
	v_pk_fma_f32 v[2:3], v[2:3], v[16:17], v[24:25]
	v_pk_fma_f32 v[0:1], v[0:1], v[14:15], v[22:23]
	s_nop 0
	v_cvt_pk_bf16_f32 v0, v0, v1
	v_cvt_pk_bf16_f32 v1, v2, v3
	global_store_dwordx2 v[62:63], v[0:1], off offset:1536
	v_pk_mul_f32 v[0:1], v[4:5], v[144:145] op_sel_hi:[1,0]
	v_pk_mul_f32 v[2:3], v[6:7], v[144:145] op_sel_hi:[1,0]
	v_pk_fma_f32 v[0:1], v[0:1], v[14:15], v[22:23]
	v_pk_fma_f32 v[2:3], v[2:3], v[16:17], v[24:25]
	v_cvt_pk_bf16_f32 v0, v0, v1
	v_cvt_pk_bf16_f32 v1, v2, v3
	global_store_dwordx2 v[64:65], v[0:1], off offset:1536
	v_pk_mul_f32 v[0:1], v[10:11], v[146:147] op_sel_hi:[1,0]
	v_pk_mul_f32 v[2:3], v[12:13], v[146:147] op_sel_hi:[1,0]
	v_pk_fma_f32 v[0:1], v[0:1], v[14:15], v[22:23]
	v_pk_fma_f32 v[2:3], v[2:3], v[16:17], v[24:25]
	v_cvt_pk_bf16_f32 v0, v0, v1
	v_cvt_pk_bf16_f32 v1, v2, v3
	global_store_dwordx2 v[78:79], v[0:1], off offset:1536
	v_pk_mul_f32 v[0:1], v[18:19], v[148:149] op_sel_hi:[1,0]
	v_pk_mul_f32 v[2:3], v[20:21], v[148:149] op_sel_hi:[1,0]
	v_pk_fma_f32 v[0:1], v[0:1], v[14:15], v[22:23]
	v_pk_fma_f32 v[2:3], v[2:3], v[16:17], v[24:25]
	v_cvt_pk_bf16_f32 v0, v0, v1
	v_cvt_pk_bf16_f32 v1, v2, v3
	global_store_dwordx2 v[80:81], v[0:1], off offset:1536
	v_pk_mul_f32 v[0:1], v[26:27], v[150:151] op_sel_hi:[1,0]
	v_pk_mul_f32 v[2:3], v[28:29], v[150:151] op_sel_hi:[1,0]
	v_pk_fma_f32 v[0:1], v[0:1], v[14:15], v[22:23]
	v_pk_fma_f32 v[2:3], v[2:3], v[16:17], v[24:25]
	v_cvt_pk_bf16_f32 v0, v0, v1
	v_cvt_pk_bf16_f32 v1, v2, v3
	global_store_dwordx2 v[90:91], v[0:1], off offset:1536
	v_pk_mul_f32 v[0:1], v[38:39], v[152:153] op_sel_hi:[1,0]
	v_pk_mul_f32 v[2:3], v[40:41], v[152:153] op_sel_hi:[1,0]
	v_pk_fma_f32 v[0:1], v[0:1], v[14:15], v[22:23]
	v_pk_fma_f32 v[2:3], v[2:3], v[16:17], v[24:25]
	v_cvt_pk_bf16_f32 v0, v0, v1
	v_cvt_pk_bf16_f32 v1, v2, v3
	global_store_dwordx2 v[92:93], v[0:1], off offset:1536
	v_pk_mul_f32 v[0:1], v[50:51], v[154:155] op_sel_hi:[1,0]
	v_pk_mul_f32 v[2:3], v[52:53], v[154:155] op_sel_hi:[1,0]
	v_pk_fma_f32 v[0:1], v[0:1], v[14:15], v[22:23]
	v_pk_fma_f32 v[2:3], v[2:3], v[16:17], v[24:25]
	v_cvt_pk_bf16_f32 v0, v0, v1
	v_cvt_pk_bf16_f32 v1, v2, v3
	global_store_dwordx2 v[98:99], v[0:1], off offset:1536
	v_pk_mul_f32 v[0:1], v[74:75], v[156:157] op_sel_hi:[1,0]
	v_pk_mul_f32 v[2:3], v[76:77], v[156:157] op_sel_hi:[1,0]
	v_pk_fma_f32 v[0:1], v[0:1], v[14:15], v[22:23]
	v_pk_fma_f32 v[2:3], v[2:3], v[16:17], v[24:25]
	v_cvt_pk_bf16_f32 v0, v0, v1
	v_cvt_pk_bf16_f32 v1, v2, v3
	global_store_dwordx2 v[100:101], v[0:1], off offset:1536

.Lxg_7:
	flat_load_dword v234, v[2:3] sc1
	s_waitcnt vmcnt(0) lgkmcnt(0)
	v_cmp_ne_u32_e32 vcc, v234, v1
	s_cbranch_vccz .Lxg_7
	s_waitcnt vmcnt(0)
	s_branch .Ltramp_7

.LBB0_1402:
	s_cmp_eq_u32 s100, 0
	s_cbranch_scc1 .Lfl_7
	s_add_i32 s82, s6, 0x900
	s_lshl_b64 s[10:11], s[82:83], 2
	s_add_u32 s10, s42, s10
	s_addc_u32 s11, s43, s11
	v_mov_b64_e32 v[0:1], s[10:11]
	flat_atomic_add v[0:1], v228
	s_waitcnt vmcnt(0)
	s_branch .Ltramp_7

.LBB0_1421:
	global_load_dwordx4 v[14:17], v[2:3], off offset:-3072 sc1
	global_load_dwordx4 v[18:21], v[2:3], off offset:-2048 sc1
	global_load_dwordx4 v[22:25], v[2:3], off sc1
	global_load_dwordx4 v[26:29], v[2:3], off offset:-1024 sc1
	global_load_dwordx4 v[30:33], v[0:1], off sc1
	s_add_i32 s6, s6, s80
	s_cmpk_lt_i32 s6, 0x4000
	s_waitcnt vmcnt(0)
	v_pk_mul_f32 v[34:35], v[16:17], v[16:17]
	v_pk_mul_f32 v[36:37], v[14:15], v[14:15]
	v_pk_mul_f32 v[38:39], v[20:21], v[20:21]
	v_pk_mul_f32 v[40:41], v[18:19], v[18:19]
	v_pk_mov_b32 v[46:47], v[36:37], v[34:35] op_sel:[1,0]
	v_mov_b32_e32 v37, v35
	v_pk_mov_b32 v[34:35], v[40:41], v[38:39] op_sel:[1,0]
	v_mov_b32_e32 v41, v39
	v_mul_f32_e32 v45, v23, v23
	v_mul_f32_e32 v42, v27, v27
	v_mul_f32_e32 v44, v29, v29
	v_pk_add_f32 v[36:37], v[46:47], v[36:37]
	v_pk_add_f32 v[34:35], v[34:35], v[40:41]
	v_mul_f32_e32 v13, v22, v22
	v_mul_f32_e32 v48, v24, v24
	v_mul_f32_e32 v49, v25, v25
	v_pk_fma_f32 v[38:39], v[26:27], v[26:27], v[42:43] op_sel_hi:[1,1,0]
	v_pk_fma_f32 v[42:43], v[28:29], v[28:29], v[44:45] op_sel_hi:[1,1,0]
	v_pk_add_f32 v[36:37], v[36:37], v[36:37] op_sel:[0,1] op_sel_hi:[1,0]
	v_pk_add_f32 v[34:35], v[34:35], v[34:35] op_sel:[0,1] op_sel_hi:[1,0]
	v_mov_b32_e32 v39, v48
	v_mov_b32_e32 v43, v49
	v_mov_b32_e32 v37, v13
	v_mov_b32_e32 v35, v45
	v_pk_add_f32 v[38:39], v[38:39], v[42:43]
	v_pk_add_f32 v[34:35], v[36:37], v[34:35]
	s_nop 0
	v_pk_add_f32 v[34:35], v[34:35], v[38:39]
	s_nop 0
	v_add_f32_e32 v13, v34, v35
	ds_bpermute_b32 v34, v5, v13
	s_waitcnt lgkmcnt(0)
	v_add_f32_e32 v13, v13, v34
	ds_bpermute_b32 v34, v6, v13
	s_waitcnt lgkmcnt(0)
	v_add_f32_e32 v13, v13, v34
	ds_bpermute_b32 v34, v7, v13
	s_waitcnt lgkmcnt(0)
	v_add_f32_e32 v13, v13, v34
	ds_bpermute_b32 v34, v8, v13
	s_waitcnt lgkmcnt(0)
	v_add_f32_e32 v13, v13, v34
	ds_bpermute_b32 v34, v9, v13
	s_waitcnt lgkmcnt(0)
	v_add_f32_e32 v13, v13, v34
	ds_bpermute_b32 v34, v10, v13
	s_waitcnt lgkmcnt(0)
	v_add_f32_e32 v13, v13, v34
	v_fmamk_f32 v13, v13, 0x3a800000, v11
	v_mul_f32_e32 v34, 0x4f800000, v13
	v_cmp_gt_f32_e32 vcc, s2, v13
	s_nop 1
	v_cndmask_b32_e32 v13, v13, v34, vcc
	v_sqrt_f32_e32 v34, v13
	s_nop 0
	v_add_u32_e32 v35, -1, v34
	v_add_u32_e32 v36, 1, v34
	v_fma_f32 v37, -v35, v34, v13
	v_fma_f32 v38, -v36, v34, v13
	v_cmp_ge_f32_e64 s[0:1], 0, v37
	s_nop 1
	v_cndmask_b32_e64 v34, v34, v35, s[0:1]
	v_cmp_lt_f32_e64 s[0:1], 0, v38
	s_nop 1
	v_cndmask_b32_e64 v34, v34, v36, s[0:1]
	v_mul_f32_e32 v35, 0x37800000, v34
	v_cndmask_b32_e32 v34, v34, v35, vcc
	v_cmp_class_f32_e32 vcc, v13, v12
	s_nop 1
	v_cndmask_b32_e32 v13, v34, v13, vcc
	v_div_scale_f32 v34, s[0:1], v13, v13, 1.0
	v_rcp_f32_e32 v35, v34
	v_div_scale_f32 v36, vcc, 1.0, v13, 1.0
	v_fma_f32 v37, -v34, v35, 1.0
	v_fmac_f32_e32 v35, v37, v35
	v_mul_f32_e32 v37, v36, v35
	v_fma_f32 v38, -v34, v37, v36
	v_fmac_f32_e32 v37, v38, v35
	v_fma_f32 v34, -v34, v37, v36
	v_div_fmas_f32 v34, v34, v35, v37
	v_div_fixup_f32 v34, v34, v13, 1.0
	v_pk_mul_f32 v[14:15], v[14:15], v[34:35] op_sel_hi:[1,0]
	v_pk_mul_f32 v[16:17], v[16:17], v[34:35] op_sel_hi:[1,0]
	v_pk_mul_f32 v[14:15], v[30:31], v[14:15]
	v_pk_mul_f32 v[16:17], v[32:33], v[16:17]
	global_store_dwordx4 v[2:3], v[14:17], off offset:-3072
	global_load_dwordx4 v[14:17], v[0:1], off offset:1024 sc1
	v_pk_mul_f32 v[20:21], v[20:21], v[34:35] op_sel_hi:[1,0]
	v_pk_mul_f32 v[18:19], v[18:19], v[34:35] op_sel_hi:[1,0]
	s_waitcnt vmcnt(0)
	v_pk_mul_f32 v[16:17], v[16:17], v[20:21]
	v_pk_mul_f32 v[14:15], v[14:15], v[18:19]
	global_store_dwordx4 v[2:3], v[14:17], off offset:-2048
	global_load_dwordx4 v[14:17], v[0:1], off offset:2048 sc1
	v_pk_mul_f32 v[18:19], v[28:29], v[34:35] op_sel_hi:[1,0]
	v_pk_mul_f32 v[20:21], v[26:27], v[34:35] op_sel_hi:[1,0]
	s_waitcnt vmcnt(0)
	v_pk_mul_f32 v[16:17], v[16:17], v[18:19]
	v_pk_mul_f32 v[14:15], v[14:15], v[20:21]
	global_store_dwordx4 v[2:3], v[14:17], off offset:-1024
	global_load_dwordx4 v[14:17], v[0:1], off offset:3072 sc1
	v_pk_mul_f32 v[18:19], v[24:25], v[34:35] op_sel_hi:[1,0]
	v_pk_mul_f32 v[20:21], v[22:23], v[34:35] op_sel_hi:[1,0]
	s_waitcnt vmcnt(0)
	v_pk_mul_f32 v[16:17], v[16:17], v[18:19]
	v_pk_mul_f32 v[14:15], v[14:15], v[20:21]
	global_store_dwordx4 v[2:3], v[14:17], off
	v_lshl_add_u64 v[2:3], v[2:3], 0, s[8:9]
	s_cbranch_scc1 .LBB0_1421

.LBB0_1423:
	v_lshlrev_b32_e32 v24, 2, v4
	v_ashrrev_i32_e32 v25, 31, v24
	v_readlane_b32 s0, v251, 31
	v_lshlrev_b64 v[64:65], 2, v[24:25]
	s_waitcnt lgkmcnt(0)
	v_lshl_add_u64 v[100:101], s[4:5], 0, v[64:65]
	global_load_dwordx4 v[104:107], v[100:101], off sc1
	global_load_dwordx4 v[108:111], v[100:101], off offset:1024 sc1
	global_load_dwordx4 v[112:115], v[100:101], off offset:2048 sc1
	global_load_dwordx4 v[116:119], v[100:101], off offset:3072 sc1
	v_readlane_b32 s1, v251, 32
	v_lshl_add_u64 v[68:69], s[44:45], 0, v[64:65]
	s_lshl_b64 s[10:11], s[0:1], 12
	v_readlane_b32 s0, v251, 35
	v_lshl_add_u64 v[0:1], v[68:69], 0, s[10:11]
	v_readlane_b32 s1, v251, 36
	global_load_dwordx4 v[44:47], v[0:1], off sc1
	global_load_dwordx4 v[32:35], v[0:1], off offset:1024 sc1
	global_load_dwordx4 v[8:11], v[0:1], off offset:3072 sc1
	global_load_dwordx4 v[12:15], v[0:1], off offset:2048 sc1
	s_lshl_b64 s[8:9], s[0:1], 12
	v_lshl_add_u64 v[4:5], v[68:69], 0, s[8:9]
	global_load_dwordx4 v[40:43], v[4:5], off sc1
	global_load_dwordx4 v[28:31], v[4:5], off offset:1024 sc1
	global_load_dwordx4 v[0:3], v[4:5], off offset:3072 sc1
	global_load_dwordx4 v[16:19], v[4:5], off offset:2048 sc1
	v_readlane_b32 s0, v251, 39
	v_readlane_b32 s1, v251, 40
	s_lshl_b64 s[6:7], s[0:1], 12
	v_lshl_add_u64 v[26:27], v[68:69], 0, s[6:7]
	global_load_dwordx4 v[48:51], v[26:27], off sc1
	global_load_dwordx4 v[36:39], v[26:27], off offset:1024 sc1
	global_load_dwordx4 v[20:23], v[26:27], off offset:2048 sc1
	global_load_dwordx4 v[4:7], v[26:27], off offset:3072 sc1
	v_xor_b32_e32 v71, 4, v24
	v_readlane_b32 s0, v251, 43
	v_readlane_b32 s1, v251, 44
	s_lshl_b64 s[12:13], s[0:1], 12
	s_mov_b32 s14, 0xf800000
	s_waitcnt vmcnt(0)
	v_pk_mul_f32 v[26:27], v[46:47], v[46:47]
	v_pk_mul_f32 v[52:53], v[44:45], v[44:45]
	v_pk_mul_f32 v[54:55], v[34:35], v[34:35]
	v_pk_mul_f32 v[56:57], v[32:33], v[32:33]
	v_mul_f32_e32 v58, v13, v13
	v_mul_f32_e32 v60, v15, v15
	v_pk_mul_f32 v[62:63], v[42:43], v[42:43]
	v_pk_mul_f32 v[66:67], v[40:41], v[40:41]
	v_pk_mul_f32 v[72:73], v[30:31], v[30:31]
	v_pk_mul_f32 v[74:75], v[28:29], v[28:29]
	v_pk_mov_b32 v[78:79], v[52:53], v[26:27] op_sel:[1,0]
	v_mov_b32_e32 v53, v27
	v_pk_mov_b32 v[26:27], v[56:57], v[54:55] op_sel:[1,0]
	v_mov_b32_e32 v57, v55
	v_mul_f32_e32 v81, v10, v10
	v_mul_f32_e32 v82, v11, v11
	v_pk_fma_f32 v[54:55], v[12:13], v[12:13], v[58:59] op_sel_hi:[1,1,0]
	v_pk_fma_f32 v[58:59], v[14:15], v[14:15], v[60:61] op_sel_hi:[1,1,0]
	v_pk_mov_b32 v[60:61], v[66:67], v[62:63] op_sel:[1,0]
	v_mov_b32_e32 v67, v63
	v_pk_mov_b32 v[62:63], v[74:75], v[72:73] op_sel:[1,0]
	v_mov_b32_e32 v75, v73
	v_pk_add_f32 v[52:53], v[78:79], v[52:53]
	v_pk_add_f32 v[26:27], v[26:27], v[56:57]
	v_mul_f32_e32 v25, v8, v8
	v_mul_f32_e32 v80, v9, v9
	v_mul_f32_e32 v70, v17, v17
	v_mul_f32_e32 v76, v19, v19
	v_mov_b32_e32 v55, v81
	v_mov_b32_e32 v59, v82
	v_pk_add_f32 v[56:57], v[60:61], v[66:67]
	v_pk_add_f32 v[60:61], v[62:63], v[74:75]
	v_pk_add_f32 v[52:53], v[52:53], v[52:53] op_sel:[0,1] op_sel_hi:[1,0]
	v_pk_add_f32 v[26:27], v[26:27], v[26:27] op_sel:[0,1] op_sel_hi:[1,0]
	v_mul_f32_e32 v83, v0, v0
	v_mul_f32_e32 v84, v1, v1
	v_mul_f32_e32 v85, v2, v2
	v_mul_f32_e32 v86, v3, v3
	v_pk_fma_f32 v[72:73], v[16:17], v[16:17], v[70:71] op_sel_hi:[1,1,0]
	v_pk_fma_f32 v[76:77], v[18:19], v[18:19], v[76:77] op_sel_hi:[1,1,0]
	v_pk_add_f32 v[54:55], v[54:55], v[58:59]
	v_pk_add_f32 v[56:57], v[56:57], v[56:57] op_sel:[0,1] op_sel_hi:[1,0]
	v_pk_add_f32 v[58:59], v[60:61], v[60:61] op_sel:[0,1] op_sel_hi:[1,0]
	v_mov_b32_e32 v53, v25
	v_mov_b32_e32 v27, v80
	v_mov_b32_e32 v73, v85
	v_mov_b32_e32 v77, v86
	v_mov_b32_e32 v57, v83
	v_mov_b32_e32 v59, v84
	v_pk_add_f32 v[26:27], v[52:53], v[26:27]
	v_pk_add_f32 v[60:61], v[72:73], v[76:77]
	v_pk_add_f32 v[52:53], v[56:57], v[58:59]
	v_pk_add_f32 v[26:27], v[26:27], v[54:55]
	v_pk_add_f32 v[52:53], v[52:53], v[60:61]
	v_add_f32_e32 v25, v26, v27
	v_add_f32_e32 v26, v52, v53
	ds_bpermute_b32 v27, v71, v25
	ds_bpermute_b32 v52, v71, v26
	v_xor_b32_e32 v79, 8, v24
	v_xor_b32_e32 v81, 16, v24
	v_xor_b32_e32 v80, 32, v24
	s_waitcnt lgkmcnt(0)
	v_add_f32_e32 v25, v25, v27
	v_add_f32_e32 v26, v26, v52
	ds_bpermute_b32 v27, v79, v25
	ds_bpermute_b32 v52, v79, v26
	v_xor_b32_e32 v78, 64, v24
	v_xor_b32_e32 v77, 0x80, v24
	v_lshl_add_u64 v[66:67], v[68:69], 0, s[12:13]
	s_waitcnt lgkmcnt(1)
	v_add_f32_e32 v25, v25, v27
	s_waitcnt lgkmcnt(0)
	v_add_f32_e32 v26, v26, v52
	ds_bpermute_b32 v27, v81, v25
	ds_bpermute_b32 v52, v81, v26
	global_load_dwordx4 v[60:63], v[66:67], off sc1
	global_load_dwordx4 v[56:59], v[66:67], off offset:1024 sc1
	v_pk_mul_f32 v[82:83], v[48:49], v[48:49]
	v_mov_b32_e32 v75, 0x358637bd
	s_waitcnt lgkmcnt(1)
	v_add_f32_e32 v24, v25, v27
	s_waitcnt lgkmcnt(0)
	v_add_f32_e32 v25, v26, v52
	ds_bpermute_b32 v26, v80, v24
	ds_bpermute_b32 v27, v80, v25
	v_mov_b32_e32 v73, 0x260
	s_waitcnt lgkmcnt(1)
	v_add_f32_e32 v70, v24, v26
	ds_bpermute_b32 v74, v78, v70
	s_waitcnt lgkmcnt(1)
	v_add_f32_e32 v72, v25, v27
	ds_bpermute_b32 v76, v78, v72
	global_load_dwordx4 v[52:55], v[66:67], off offset:2048 sc1
	global_load_dwordx4 v[24:27], v[66:67], off offset:3072 sc1
	v_pk_mul_f32 v[66:67], v[50:51], v[50:51]
	s_waitcnt lgkmcnt(1)
	v_add_f32_e32 v70, v70, v74
	ds_bpermute_b32 v74, v77, v70
	s_waitcnt lgkmcnt(1)
	v_add_f32_e32 v72, v72, v76
	ds_bpermute_b32 v76, v77, v72
	v_pk_mov_b32 v[84:85], v[82:83], v[66:67] op_sel:[1,0]
	v_mov_b32_e32 v83, v67
	s_waitcnt lgkmcnt(1)
	v_add_f32_e32 v66, v70, v74
	v_fmamk_f32 v66, v66, 0x3a800000, v75
	v_mul_f32_e32 v70, 0x4f800000, v66
	v_cmp_gt_f32_e32 vcc, s14, v66
	s_waitcnt lgkmcnt(0)
	v_add_f32_e32 v67, v72, v76
	v_fmamk_f32 v67, v67, 0x3a800000, v75
	v_cndmask_b32_e32 v66, v66, v70, vcc
	v_sqrt_f32_e32 v70, v66
	v_mul_f32_e32 v72, 0x4f800000, v67
	v_cmp_gt_f32_e64 s[0:1], s14, v67
	v_add_u32_e32 v74, 1, v70
	s_nop 0
	v_cndmask_b32_e64 v72, v67, v72, s[0:1]
	v_add_u32_e32 v67, -1, v70
	v_fma_f32 v76, -v67, v70, v66
	v_fma_f32 v86, -v74, v70, v66
	v_cmp_ge_f32_e64 s[2:3], 0, v76
	v_sqrt_f32_e32 v89, v72
	s_waitcnt vmcnt(0)
	v_mul_f32_e32 v97, v27, v27
	v_cndmask_b32_e64 v67, v70, v67, s[2:3]
	v_cmp_lt_f32_e64 s[2:3], 0, v86
	s_nop 1
	v_cndmask_b32_e64 v67, v67, v74, s[2:3]
	v_mul_f32_e32 v70, 0x37800000, v67
	v_cndmask_b32_e32 v67, v67, v70, vcc
	v_cmp_class_f32_e32 vcc, v66, v73
	v_mul_f32_e32 v70, v4, v4
	s_nop 0
	v_cndmask_b32_e32 v74, v67, v66, vcc
	v_div_scale_f32 v76, s[2:3], v74, v74, 1.0
	v_rcp_f32_e32 v88, v76
	v_div_scale_f32 v90, vcc, 1.0, v74, 1.0
	v_fma_f32 v66, -v76, v88, 1.0
	v_fmac_f32_e32 v88, v66, v88
	v_pk_add_f32 v[66:67], v[84:85], v[82:83]
	v_pk_mul_f32 v[82:83], v[38:39], v[38:39]
	v_pk_mul_f32 v[84:85], v[36:37], v[36:37]
	v_pk_add_f32 v[66:67], v[66:67], v[66:67] op_sel:[0,1] op_sel_hi:[1,0]
	v_pk_mov_b32 v[86:87], v[84:85], v[82:83] op_sel:[1,0]
	v_mov_b32_e32 v85, v83
	v_pk_add_f32 v[82:83], v[86:87], v[84:85]
	v_mul_f32_e32 v84, v5, v5
	v_pk_add_f32 v[82:83], v[82:83], v[82:83] op_sel:[0,1] op_sel_hi:[1,0]
	v_mov_b32_e32 v67, v70
	v_mov_b32_e32 v83, v84
	v_mul_f32_e32 v70, v21, v21
	v_mul_f32_e32 v85, v6, v6
	v_pk_add_f32 v[66:67], v[66:67], v[82:83]
	v_pk_fma_f32 v[82:83], v[20:21], v[20:21], v[70:71] op_sel_hi:[1,1,0]
	v_mul_f32_e32 v70, v23, v23
	v_mul_f32_e32 v86, v7, v7
	v_mov_b32_e32 v83, v85
	v_pk_fma_f32 v[84:85], v[22:23], v[22:23], v[70:71] op_sel_hi:[1,1,0]
	v_mul_f32_e32 v91, v90, v88
	v_mov_b32_e32 v85, v86
	v_pk_add_f32 v[82:83], v[82:83], v[84:85]
	v_fma_f32 v92, -v76, v91, v90
	v_pk_add_f32 v[66:67], v[66:67], v[82:83]
	v_fmac_f32_e32 v91, v92, v88
	v_add_f32_e32 v66, v66, v67
	ds_bpermute_b32 v67, v71, v66
	v_fma_f32 v70, -v76, v91, v90
	v_add_u32_e32 v76, -1, v89
	v_fma_f32 v82, -v76, v89, v72
	v_cmp_ge_f32_e64 s[2:3], 0, v82
	s_waitcnt lgkmcnt(0)
	v_add_f32_e32 v66, v66, v67
	ds_bpermute_b32 v67, v79, v66
	v_add_u32_e32 v82, 1, v89
	v_fma_f32 v83, -v82, v89, v72
	v_cndmask_b32_e64 v76, v89, v76, s[2:3]
	v_cmp_lt_f32_e64 s[2:3], 0, v83
	s_waitcnt lgkmcnt(0)
	v_add_f32_e32 v66, v66, v67
	ds_bpermute_b32 v67, v81, v66
	v_cndmask_b32_e64 v76, v76, v82, s[2:3]
	v_mul_f32_e32 v82, 0x37800000, v76
	v_cndmask_b32_e64 v76, v76, v82, s[0:1]
	v_cmp_class_f32_e64 s[0:1], v72, v73
	s_waitcnt lgkmcnt(0)
	v_add_f32_e32 v66, v66, v67
	ds_bpermute_b32 v67, v80, v66
	v_cndmask_b32_e64 v72, v76, v72, s[0:1]
	v_div_scale_f32 v76, s[0:1], v72, v72, 1.0
	v_pk_mul_f32 v[82:83], v[60:61], v[60:61]
	s_waitcnt lgkmcnt(0)
	v_add_f32_e32 v66, v66, v67
	ds_bpermute_b32 v67, v78, v66
	v_div_fmas_f32 v70, v70, v88, v91
	v_mul_f32_e32 v90, v26, v26
	v_rcp_f32_e32 v92, v76
	v_div_fixup_f32 v70, v70, v74, 1.0
	s_waitcnt lgkmcnt(0)
	v_add_f32_e32 v66, v66, v67
	ds_bpermute_b32 v67, v77, v66
	v_fma_f32 v74, -v76, v92, 1.0
	v_fmac_f32_e32 v92, v74, v92
	v_div_scale_f32 v74, vcc, 1.0, v72, 1.0
	s_waitcnt lgkmcnt(0)
	v_add_f32_e32 v66, v66, v67
	v_fmamk_f32 v66, v66, 0x3a800000, v75
	v_mul_f32_e32 v67, 0x4f800000, v66
	v_cmp_gt_f32_e64 s[0:1], s14, v66
	v_mul_f32_e32 v93, v74, v92
	v_fma_f32 v94, -v76, v93, v74
	v_cndmask_b32_e64 v95, v66, v67, s[0:1]
	v_pk_mul_f32 v[66:67], v[62:63], v[62:63]
	v_sqrt_f32_e32 v96, v95
	v_pk_mov_b32 v[84:85], v[82:83], v[66:67] op_sel:[1,0]
	v_mov_b32_e32 v83, v67
	v_pk_add_f32 v[66:67], v[84:85], v[82:83]
	v_pk_mul_f32 v[82:83], v[58:59], v[58:59]
	v_pk_mul_f32 v[84:85], v[56:57], v[56:57]
	v_pk_add_f32 v[66:67], v[66:67], v[66:67] op_sel:[0,1] op_sel_hi:[1,0]
	v_pk_mov_b32 v[86:87], v[84:85], v[82:83] op_sel:[1,0]
	v_mov_b32_e32 v85, v83
	v_pk_add_f32 v[82:83], v[86:87], v[84:85]
	v_mul_f32_e32 v84, v24, v24
	v_mul_f32_e32 v85, v25, v25
	v_pk_add_f32 v[82:83], v[82:83], v[82:83] op_sel:[0,1] op_sel_hi:[1,0]
	v_mov_b32_e32 v67, v84
	v_mov_b32_e32 v83, v85
	v_pk_add_f32 v[86:87], v[66:67], v[82:83]
	v_mul_f32_e32 v66, v53, v53
	v_pk_fma_f32 v[88:89], v[52:53], v[52:53], v[66:67] op_sel_hi:[1,1,0]
	v_mul_f32_e32 v66, v55, v55
	v_mov_b32_e32 v89, v90
	v_pk_fma_f32 v[90:91], v[54:55], v[54:55], v[66:67] op_sel_hi:[1,1,0]
	v_lshl_add_u64 v[66:67], s[4:5], 0, v[64:65]
	global_load_dwordx4 v[82:85], v[66:67], off sc1
	v_mov_b32_e32 v91, v97
	v_pk_add_f32 v[88:89], v[88:89], v[90:91]
	v_fmac_f32_e32 v93, v94, v92
	v_pk_add_f32 v[86:87], v[86:87], v[88:89]
	v_fma_f32 v74, -v76, v93, v74
	v_add_f32_e32 v86, v86, v87
	ds_bpermute_b32 v87, v71, v86
	v_add_u32_e32 v76, -1, v96
	v_fma_f32 v88, -v76, v96, v95
	v_cmp_ge_f32_e64 s[2:3], 0, v88
	v_add_u32_e32 v88, 1, v96
	s_waitcnt lgkmcnt(0)
	v_add_f32_e32 v86, v86, v87
	ds_bpermute_b32 v87, v79, v86
	v_fma_f32 v89, -v88, v96, v95
	v_cndmask_b32_e64 v76, v96, v76, s[2:3]
	v_cmp_lt_f32_e64 s[2:3], 0, v89
	v_div_fmas_f32 v74, v74, v92, v93
	s_waitcnt lgkmcnt(0)
	v_add_f32_e32 v86, v86, v87
	ds_bpermute_b32 v87, v81, v86
	v_cndmask_b32_e64 v76, v76, v88, s[2:3]
	v_mul_f32_e32 v88, 0x37800000, v76
	v_cndmask_b32_e64 v76, v76, v88, s[0:1]
	v_cmp_class_f32_e64 s[0:1], v95, v73
	s_waitcnt lgkmcnt(0)
	v_add_f32_e32 v86, v86, v87
	ds_bpermute_b32 v87, v80, v86
	v_cndmask_b32_e64 v76, v76, v95, s[0:1]
	v_div_scale_f32 v88, s[0:1], v76, v76, 1.0
	v_rcp_f32_e32 v89, v88
	s_waitcnt lgkmcnt(0)
	v_add_f32_e32 v86, v86, v87
	ds_bpermute_b32 v87, v78, v86
	v_div_fixup_f32 v72, v74, v72, 1.0
	v_fma_f32 v74, -v88, v89, 1.0
	v_fmac_f32_e32 v89, v74, v89
	v_div_scale_f32 v74, vcc, 1.0, v76, 1.0
	s_waitcnt lgkmcnt(0)
	v_add_f32_e32 v86, v86, v87
	ds_bpermute_b32 v87, v77, v86
	v_mul_f32_e32 v90, v74, v89
	v_fma_f32 v91, -v88, v90, v74
	v_fmac_f32_e32 v90, v91, v89
	v_fma_f32 v74, -v88, v90, v74
	s_waitcnt lgkmcnt(0)
	v_add_f32_e32 v86, v86, v87
	v_fmamk_f32 v86, v86, 0x3a800000, v75
	v_mul_f32_e32 v87, 0x4f800000, v86
	v_cmp_gt_f32_e64 s[0:1], s14, v86
	v_div_fmas_f32 v74, v74, v89, v90
	v_div_fixup_f32 v74, v74, v76, 1.0
	v_cndmask_b32_e64 v86, v86, v87, s[0:1]
	v_sqrt_f32_e32 v87, v86
	v_pk_mul_f32 v[44:45], v[44:45], v[70:71] op_sel_hi:[1,0]
	v_pk_mul_f32 v[46:47], v[46:47], v[70:71] op_sel_hi:[1,0]
	v_pk_mul_f32 v[40:41], v[40:41], v[72:73] op_sel_hi:[1,0]
	v_add_u32_e32 v88, -1, v87
	v_fma_f32 v91, -v88, v87, v86
	v_cmp_ge_f32_e64 s[2:3], 0, v91
	v_add_u32_e32 v91, 1, v87
	v_pk_mul_f32 v[42:43], v[42:43], v[72:73] op_sel_hi:[1,0]
	v_cndmask_b32_e64 v88, v87, v88, s[2:3]
	v_fma_f32 v87, -v91, v87, v86
	v_cmp_lt_f32_e64 s[2:3], 0, v87
	v_pk_mul_f32 v[30:31], v[30:31], v[72:73] op_sel_hi:[1,0]
	v_pk_mul_f32 v[28:29], v[28:29], v[72:73] op_sel_hi:[1,0]
	v_cndmask_b32_e64 v87, v88, v91, s[2:3]
	v_mul_f32_e32 v88, 0x37800000, v87
	v_cndmask_b32_e64 v87, v87, v88, s[0:1]
	v_cmp_class_f32_e64 s[0:1], v86, v73
	v_pk_mul_f32 v[34:35], v[34:35], v[70:71] op_sel_hi:[1,0]
	v_pk_mul_f32 v[32:33], v[32:33], v[70:71] op_sel_hi:[1,0]
	v_cndmask_b32_e64 v86, v87, v86, s[0:1]
	v_div_scale_f32 v87, s[0:1], v86, v86, 1.0
	v_rcp_f32_e32 v88, v87
	s_add_u32 s0, s44, s10
	s_addc_u32 s1, s45, s11
	v_pk_mul_f32 v[18:19], v[18:19], v[72:73] op_sel_hi:[1,0]
	v_fma_f32 v76, -v87, v88, 1.0
	v_fmac_f32_e32 v88, v76, v88
	v_div_scale_f32 v76, vcc, 1.0, v86, 1.0
	v_mul_f32_e32 v89, v76, v88
	v_fma_f32 v90, -v87, v89, v76
	v_fmac_f32_e32 v89, v90, v88
	v_fma_f32 v76, -v87, v89, v76
	v_div_fmas_f32 v76, v76, v88, v89
	v_div_fixup_f32 v76, v76, v86, 1.0
	s_waitcnt vmcnt(0)
	v_pk_mul_f32 v[86:87], v[44:45], v[82:83]
	v_lshl_add_u64 v[44:45], s[0:1], 0, v[64:65]
	s_add_u32 s0, s44, s8
	s_addc_u32 s1, s45, s9
	v_pk_mul_f32 v[88:89], v[46:47], v[84:85]
	v_pk_mul_f32 v[42:43], v[42:43], v[84:85]
	v_pk_mul_f32 v[40:41], v[40:41], v[82:83]
	v_lshl_add_u64 v[46:47], s[0:1], 0, v[64:65]
	s_add_u32 s0, s44, s6
	global_store_dwordx4 v[46:47], v[40:43], off nt
	s_addc_u32 s1, s45, s7
	global_store_dwordx4 v[44:45], v[86:89], off nt
	v_pk_mul_f32 v[40:41], v[48:49], v[74:75] op_sel_hi:[1,0]
	v_pk_mul_f32 v[42:43], v[50:51], v[74:75] op_sel_hi:[1,0]
	v_pk_mul_f32 v[40:41], v[82:83], v[40:41]
	v_pk_mul_f32 v[42:43], v[84:85], v[42:43]
	v_lshl_add_u64 v[48:49], s[0:1], 0, v[64:65]
	s_add_u32 s0, s44, s12
	global_store_dwordx4 v[48:49], v[40:43], off nt
	s_addc_u32 s1, s45, s13
	v_lshl_add_u64 v[50:51], s[0:1], 0, v[64:65]
	v_pk_mul_f32 v[40:41], v[60:61], v[76:77] op_sel_hi:[1,0]
	v_pk_mul_f32 v[42:43], v[62:63], v[76:77] op_sel_hi:[1,0]
	v_pk_mul_f32 v[40:41], v[82:83], v[40:41]
	v_pk_mul_f32 v[42:43], v[84:85], v[42:43]
	global_store_dwordx4 v[50:51], v[40:43], off nt
	s_nop 1
	v_mov_b64_e32 v[40:41], v[108:109]
	v_mov_b64_e32 v[42:43], v[110:111]
	v_readlane_b32 s0, v251, 47
	v_readlane_b32 s1, v251, 48
	s_lshl_b64 s[4:5], s[0:1], 12
	v_pk_mul_f32 v[60:61], v[12:13], v[70:71] op_sel_hi:[1,0]
	v_pk_mul_f32 v[16:17], v[16:17], v[72:73] op_sel_hi:[1,0]
	v_readlane_b32 s0, v251, 51
	v_readlane_b32 s1, v251, 52
	s_lshl_b64 s[6:7], s[0:1], 12
	v_pk_mul_f32 v[2:3], v[2:3], v[72:73] op_sel_hi:[1,0]
	v_pk_mul_f32 v[0:1], v[0:1], v[72:73] op_sel_hi:[1,0]
	v_readlane_b32 s0, v251, 55
	v_readlane_b32 s1, v251, 56
	s_lshl_b64 s[8:9], s[0:1], 12
	v_readlane_b32 s10, v251, 23
	v_readlane_b32 s11, v251, 24
	s_nop 0
	v_pk_mul_f32 v[28:29], v[28:29], v[40:41]
	v_pk_mul_f32 v[30:31], v[30:31], v[42:43]
	global_store_dwordx4 v[46:47], v[28:31], off offset:1024 nt
	v_pk_mul_f32 v[32:33], v[32:33], v[40:41]
	v_pk_mul_f32 v[34:35], v[34:35], v[42:43]
	v_pk_mul_f32 v[30:31], v[38:39], v[74:75] op_sel_hi:[1,0]
	v_pk_mul_f32 v[28:29], v[36:37], v[74:75] op_sel_hi:[1,0]
	v_pk_mul_f32 v[30:31], v[30:31], v[42:43]
	v_pk_mul_f32 v[28:29], v[28:29], v[40:41]
	global_store_dwordx4 v[48:49], v[28:31], off offset:1024 nt
	global_store_dwordx4 v[44:45], v[32:35], off offset:1024 nt
	s_nop 0
	v_pk_mul_f32 v[30:31], v[58:59], v[76:77] op_sel_hi:[1,0]
	v_pk_mul_f32 v[28:29], v[56:57], v[76:77] op_sel_hi:[1,0]
	v_pk_mul_f32 v[30:31], v[42:43], v[30:31]
	v_pk_mul_f32 v[28:29], v[40:41], v[28:29]
	global_store_dwordx4 v[50:51], v[28:31], off offset:1024 nt
	global_load_dwordx4 v[40:43], v[66:67], off offset:2048 sc1
	v_lshl_add_u64 v[56:57], v[68:69], 0, s[4:5]
	global_load_dwordx4 v[36:39], v[56:57], off sc1
	global_load_dwordx4 v[32:35], v[56:57], off offset:1024 sc1
	v_pk_mul_f32 v[58:59], v[14:15], v[70:71] op_sel_hi:[1,0]
	global_load_dwordx4 v[28:31], v[56:57], off offset:2048 sc1
	global_load_dwordx4 v[12:15], v[56:57], off offset:3072 sc1
	s_waitcnt vmcnt(4)
	v_pk_mul_f32 v[16:17], v[16:17], v[40:41]
	v_pk_mul_f32 v[18:19], v[18:19], v[42:43]
	global_store_dwordx4 v[46:47], v[16:19], off offset:2048 nt
	v_pk_mul_f32 v[56:57], v[60:61], v[40:41]
	v_pk_mul_f32 v[58:59], v[58:59], v[42:43]
	v_pk_mul_f32 v[18:19], v[22:23], v[74:75] op_sel_hi:[1,0]
	v_pk_mul_f32 v[16:17], v[20:21], v[74:75] op_sel_hi:[1,0]
	v_pk_mul_f32 v[18:19], v[18:19], v[42:43]
	v_pk_mul_f32 v[16:17], v[16:17], v[40:41]
	global_store_dwordx4 v[48:49], v[16:19], off offset:2048 nt
	global_store_dwordx4 v[44:45], v[56:59], off offset:2048 nt
	v_pk_mul_f32 v[60:61], v[8:9], v[70:71] op_sel_hi:[1,0]
	v_pk_mul_f32 v[18:19], v[54:55], v[76:77] op_sel_hi:[1,0]
	v_pk_mul_f32 v[16:17], v[52:53], v[76:77] op_sel_hi:[1,0]
	v_pk_mul_f32 v[18:19], v[18:19], v[42:43]
	v_pk_mul_f32 v[16:17], v[16:17], v[40:41]
	global_store_dwordx4 v[50:51], v[16:19], off offset:2048 nt
	global_load_dwordx4 v[52:55], v[66:67], off offset:3072 sc1
	v_lshl_add_u64 v[56:57], v[68:69], 0, s[6:7]
	global_load_dwordx4 v[40:43], v[56:57], off sc1
	global_load_dwordx4 v[20:23], v[56:57], off offset:1024 sc1
	v_pk_mul_f32 v[58:59], v[10:11], v[70:71] op_sel_hi:[1,0]
	global_load_dwordx4 v[16:19], v[56:57], off offset:2048 sc1
	global_load_dwordx4 v[8:11], v[56:57], off offset:3072 sc1
	s_waitcnt vmcnt(12)
	v_pk_mul_f32 v[56:57], v[38:39], v[38:39]
	v_pk_mul_f32 v[62:63], v[36:37], v[36:37]
	s_waitcnt vmcnt(9)
	v_mul_f32_e32 v70, v12, v12
	v_pk_mov_b32 v[82:83], v[62:63], v[56:57] op_sel:[1,0]
	v_mov_b32_e32 v63, v57
	v_pk_add_f32 v[56:57], v[82:83], v[62:63]
	v_pk_mul_f32 v[62:63], v[34:35], v[34:35]
	v_pk_mul_f32 v[82:83], v[32:33], v[32:33]
	v_pk_add_f32 v[56:57], v[56:57], v[56:57] op_sel:[0,1] op_sel_hi:[1,0]
	v_pk_mov_b32 v[84:85], v[82:83], v[62:63] op_sel:[1,0]
	v_mov_b32_e32 v83, v63
	v_pk_add_f32 v[62:63], v[84:85], v[82:83]
	v_mul_f32_e32 v82, v13, v13
	v_pk_add_f32 v[62:63], v[62:63], v[62:63] op_sel:[0,1] op_sel_hi:[1,0]
	v_mov_b32_e32 v57, v70
	v_mov_b32_e32 v63, v82
	v_pk_add_f32 v[56:57], v[56:57], v[62:63]
	v_mul_f32_e32 v62, v29, v29
	v_mul_f32_e32 v83, v14, v14
	v_pk_fma_f32 v[62:63], v[28:29], v[28:29], v[62:63] op_sel_hi:[1,1,0]
	v_mul_f32_e32 v70, v31, v31
	v_mul_f32_e32 v84, v15, v15
	v_mov_b32_e32 v63, v83
	v_pk_fma_f32 v[82:83], v[30:31], v[30:31], v[70:71] op_sel_hi:[1,1,0]
	s_waitcnt vmcnt(4)
	v_pk_mul_f32 v[58:59], v[58:59], v[54:55]
	v_mov_b32_e32 v83, v84
	v_pk_add_f32 v[62:63], v[62:63], v[82:83]
	v_pk_mul_f32 v[0:1], v[0:1], v[52:53]
	v_pk_add_f32 v[56:57], v[56:57], v[62:63]
	v_pk_mul_f32 v[2:3], v[2:3], v[54:55]
	v_add_f32_e32 v62, v56, v57
	ds_bpermute_b32 v63, v71, v62
	v_pk_mul_f32 v[56:57], v[60:61], v[52:53]
	global_store_dwordx4 v[44:45], v[56:59], off offset:3072 nt
	global_store_dwordx4 v[46:47], v[0:3], off offset:3072 nt
	s_waitcnt lgkmcnt(0)
	v_add_f32_e32 v44, v62, v63
	ds_bpermute_b32 v45, v79, v44
	v_pk_mul_f32 v[0:1], v[4:5], v[74:75] op_sel_hi:[1,0]
	v_pk_mul_f32 v[2:3], v[6:7], v[74:75] op_sel_hi:[1,0]
	v_pk_mul_f32 v[0:1], v[0:1], v[52:53]
	v_pk_mul_f32 v[2:3], v[2:3], v[54:55]
	s_waitcnt lgkmcnt(0)
	v_add_f32_e32 v44, v44, v45
	ds_bpermute_b32 v45, v81, v44
	global_store_dwordx4 v[48:49], v[0:3], off offset:3072 nt
	s_waitcnt lgkmcnt(0)
	v_add_f32_e32 v4, v44, v45
	ds_bpermute_b32 v5, v80, v4
	v_pk_mul_f32 v[2:3], v[26:27], v[76:77] op_sel_hi:[1,0]
	v_pk_mul_f32 v[0:1], v[24:25], v[76:77] op_sel_hi:[1,0]
	v_pk_mul_f32 v[2:3], v[2:3], v[54:55]
	v_pk_mul_f32 v[0:1], v[0:1], v[52:53]
	s_waitcnt lgkmcnt(0)
	v_add_f32_e32 v4, v4, v5
	ds_bpermute_b32 v5, v78, v4
	global_store_dwordx4 v[50:51], v[0:3], off offset:3072 nt
	v_lshl_add_u64 v[44:45], v[68:69], 0, s[8:9]
	v_lshl_add_u64 v[68:69], v[68:69], 0, s[10:11]
	s_waitcnt lgkmcnt(0)
	v_add_f32_e32 v46, v4, v5
	global_load_dwordx4 v[48:51], v[44:45], off sc1
	global_load_dwordx4 v[24:27], v[44:45], off offset:1024 sc1
	global_load_dwordx4 v[4:7], v[44:45], off offset:2048 sc1
	global_load_dwordx4 v[0:3], v[44:45], off offset:3072 sc1
	ds_bpermute_b32 v47, v77, v46
	global_load_dwordx4 v[60:63], v[68:69], off sc1
	global_load_dwordx4 v[56:59], v[68:69], off offset:1024 sc1
	s_waitcnt lgkmcnt(0)
	v_add_f32_e32 v44, v46, v47
	v_fmamk_f32 v44, v44, 0x3a800000, v75
	v_mul_f32_e32 v45, 0x4f800000, v44
	v_cmp_gt_f32_e32 vcc, s14, v44
	s_waitcnt vmcnt(13)
	v_pk_mul_f32 v[46:47], v[40:41], v[40:41]
	v_cndmask_b32_e32 v70, v44, v45, vcc
	v_pk_mul_f32 v[44:45], v[42:43], v[42:43]
	v_sqrt_f32_e32 v72, v70
	v_pk_mov_b32 v[52:53], v[46:47], v[44:45] op_sel:[1,0]
	v_mov_b32_e32 v47, v45
	v_pk_add_f32 v[44:45], v[52:53], v[46:47]
	s_waitcnt vmcnt(12)
	v_pk_mul_f32 v[46:47], v[22:23], v[22:23]
	v_pk_mul_f32 v[52:53], v[20:21], v[20:21]
	v_pk_add_f32 v[44:45], v[44:45], v[44:45] op_sel:[0,1] op_sel_hi:[1,0]
	v_pk_mov_b32 v[54:55], v[52:53], v[46:47] op_sel:[1,0]
	v_mov_b32_e32 v53, v47
	v_pk_add_f32 v[46:47], v[54:55], v[52:53]
	s_waitcnt vmcnt(10)
	v_mul_f32_e32 v52, v8, v8
	v_mul_f32_e32 v53, v9, v9
	v_pk_add_f32 v[46:47], v[46:47], v[46:47] op_sel:[0,1] op_sel_hi:[1,0]
	v_mov_b32_e32 v45, v52
	v_mov_b32_e32 v47, v53
	v_pk_add_f32 v[44:45], v[44:45], v[46:47]
	v_mul_f32_e32 v46, v17, v17
	v_mul_f32_e32 v52, v19, v19
	v_mul_f32_e32 v54, v10, v10
	v_mul_f32_e32 v55, v11, v11
	v_pk_fma_f32 v[46:47], v[16:17], v[16:17], v[46:47] op_sel_hi:[1,1,0]
	v_pk_fma_f32 v[52:53], v[18:19], v[18:19], v[52:53] op_sel_hi:[1,1,0]
	v_mov_b32_e32 v47, v54
	v_mov_b32_e32 v53, v55
	v_pk_add_f32 v[46:47], v[46:47], v[52:53]
	s_nop 0
	v_pk_add_f32 v[44:45], v[44:45], v[46:47]
	v_add_u32_e32 v46, -1, v72
	v_add_f32_e32 v44, v44, v45
	ds_bpermute_b32 v45, v71, v44
	v_fma_f32 v47, -v46, v72, v70
	v_cmp_ge_f32_e64 s[0:1], 0, v47
	v_add_u32_e32 v47, 1, v72
	v_fma_f32 v52, -v47, v72, v70
	s_waitcnt lgkmcnt(0)
	v_add_f32_e32 v44, v44, v45
	ds_bpermute_b32 v45, v79, v44
	v_cndmask_b32_e64 v46, v72, v46, s[0:1]
	v_cmp_lt_f32_e64 s[0:1], 0, v52
	s_waitcnt lgkmcnt(0)
	v_add_f32_e32 v44, v44, v45
	ds_bpermute_b32 v45, v81, v44
	v_cndmask_b32_e64 v46, v46, v47, s[0:1]
	v_mul_f32_e32 v47, 0x37800000, v46
	v_cndmask_b32_e32 v46, v46, v47, vcc
	v_cmp_class_f32_e32 vcc, v70, v73
	s_waitcnt lgkmcnt(0)
	v_add_f32_e32 v44, v44, v45
	ds_bpermute_b32 v45, v80, v44
	v_cndmask_b32_e32 v72, v46, v70, vcc
	v_div_scale_f32 v74, s[0:1], v72, v72, 1.0
	v_rcp_f32_e32 v76, v74
	s_waitcnt lgkmcnt(0)
	v_add_f32_e32 v70, v44, v45
	global_load_dwordx4 v[52:55], v[68:69], off offset:2048 sc1
	global_load_dwordx4 v[44:47], v[68:69], off offset:3072 sc1
	ds_bpermute_b32 v82, v78, v70
	v_fma_f32 v68, -v74, v76, 1.0
	v_fmac_f32_e32 v76, v68, v76
	v_div_scale_f32 v88, vcc, 1.0, v72, 1.0
	s_waitcnt lgkmcnt(0)
	v_add_f32_e32 v68, v70, v82
	ds_bpermute_b32 v69, v77, v68
	v_mul_f32_e32 v89, v88, v76
	v_fma_f32 v90, -v74, v89, v88
	s_waitcnt vmcnt(7)
	v_pk_mul_f32 v[82:83], v[48:49], v[48:49]
	v_fmac_f32_e32 v89, v90, v76
	s_waitcnt lgkmcnt(0)
	v_add_f32_e32 v68, v68, v69
	v_fmamk_f32 v68, v68, 0x3a800000, v75
	v_mul_f32_e32 v69, 0x4f800000, v68
	v_cmp_gt_f32_e64 s[0:1], s14, v68
	s_waitcnt vmcnt(4)
	v_mul_f32_e32 v70, v0, v0
	s_waitcnt vmcnt(0)
	v_mul_f32_e32 v90, v46, v46
	v_cndmask_b32_e64 v91, v68, v69, s[0:1]
	v_pk_mul_f32 v[68:69], v[50:51], v[50:51]
	v_sqrt_f32_e32 v92, v91
	v_pk_mov_b32 v[84:85], v[82:83], v[68:69] op_sel:[1,0]
	v_mov_b32_e32 v83, v69
	v_pk_add_f32 v[68:69], v[84:85], v[82:83]
	v_pk_mul_f32 v[82:83], v[26:27], v[26:27]
	v_pk_mul_f32 v[84:85], v[24:25], v[24:25]
	v_pk_add_f32 v[68:69], v[68:69], v[68:69] op_sel:[0,1] op_sel_hi:[1,0]
	v_pk_mov_b32 v[86:87], v[84:85], v[82:83] op_sel:[1,0]
	v_mov_b32_e32 v85, v83
	v_pk_add_f32 v[82:83], v[86:87], v[84:85]
	v_mul_f32_e32 v84, v1, v1
	v_pk_add_f32 v[82:83], v[82:83], v[82:83] op_sel:[0,1] op_sel_hi:[1,0]
	v_mov_b32_e32 v69, v70
	v_mov_b32_e32 v83, v84
	v_mul_f32_e32 v70, v5, v5
	v_mul_f32_e32 v85, v2, v2
	v_pk_add_f32 v[68:69], v[68:69], v[82:83]
	v_pk_fma_f32 v[82:83], v[4:5], v[4:5], v[70:71] op_sel_hi:[1,1,0]
	v_mul_f32_e32 v70, v7, v7
	v_mul_f32_e32 v86, v3, v3
	v_mov_b32_e32 v83, v85
	v_pk_fma_f32 v[84:85], v[6:7], v[6:7], v[70:71] op_sel_hi:[1,1,0]
	v_fma_f32 v70, -v74, v89, v88
	v_mov_b32_e32 v85, v86
	v_pk_add_f32 v[82:83], v[82:83], v[84:85]
	v_add_u32_e32 v74, -1, v92
	v_pk_add_f32 v[68:69], v[68:69], v[82:83]
	v_fma_f32 v82, -v74, v92, v91
	v_add_f32_e32 v68, v68, v69
	ds_bpermute_b32 v69, v71, v68
	v_cmp_ge_f32_e64 s[2:3], 0, v82
	v_add_u32_e32 v82, 1, v92
	v_fma_f32 v83, -v82, v92, v91
	v_cndmask_b32_e64 v74, v92, v74, s[2:3]
	s_waitcnt lgkmcnt(0)
	v_add_f32_e32 v68, v68, v69
	ds_bpermute_b32 v69, v79, v68
	v_cmp_lt_f32_e64 s[2:3], 0, v83
	v_pk_mul_f32 v[84:85], v[60:61], v[60:61]
	v_mul_f32_e32 v96, v47, v47
	v_cndmask_b32_e64 v74, v74, v82, s[2:3]
	s_waitcnt lgkmcnt(0)
	v_add_f32_e32 v68, v68, v69
	ds_bpermute_b32 v69, v81, v68
	v_mul_f32_e32 v82, 0x37800000, v74
	v_cndmask_b32_e64 v74, v74, v82, s[0:1]
	v_cmp_class_f32_e64 s[0:1], v91, v73
	s_waitcnt lgkmcnt(0)
	v_add_f32_e32 v68, v68, v69
	ds_bpermute_b32 v69, v80, v68
	v_cndmask_b32_e64 v74, v74, v91, s[0:1]
	v_div_scale_f32 v92, s[0:1], v74, v74, 1.0
	v_rcp_f32_e32 v93, v92
	s_waitcnt lgkmcnt(0)
	v_add_f32_e32 v69, v68, v69
	ds_bpermute_b32 v82, v78, v69
	v_div_fmas_f32 v68, v70, v76, v89
	v_fma_f32 v70, -v92, v93, 1.0
	v_fmac_f32_e32 v93, v70, v93
	v_div_fixup_f32 v68, v68, v72, 1.0
	s_waitcnt lgkmcnt(0)
	v_add_f32_e32 v69, v69, v82
	ds_bpermute_b32 v70, v77, v69
	v_pk_mul_f32 v[82:83], v[62:63], v[62:63]
	v_div_scale_f32 v72, vcc, 1.0, v74, 1.0
	v_pk_mov_b32 v[86:87], v[84:85], v[82:83] op_sel:[1,0]
	v_mov_b32_e32 v85, v83
	s_waitcnt lgkmcnt(0)
	v_add_f32_e32 v69, v69, v70
	v_pk_add_f32 v[82:83], v[86:87], v[84:85]
	v_pk_mul_f32 v[84:85], v[58:59], v[58:59]
	v_pk_mul_f32 v[86:87], v[56:57], v[56:57]
	v_fmamk_f32 v69, v69, 0x3a800000, v75
	v_pk_mov_b32 v[88:89], v[86:87], v[84:85] op_sel:[1,0]
	v_mov_b32_e32 v87, v85
	v_mul_f32_e32 v70, 0x4f800000, v69
	v_cmp_gt_f32_e64 s[0:1], s14, v69
	v_pk_add_f32 v[84:85], v[88:89], v[86:87]
	v_mul_f32_e32 v86, v45, v45
	v_cndmask_b32_e64 v69, v69, v70, s[0:1]
	v_mul_f32_e32 v70, v44, v44
	v_pk_add_f32 v[82:83], v[82:83], v[82:83] op_sel:[0,1] op_sel_hi:[1,0]
	v_pk_add_f32 v[84:85], v[84:85], v[84:85] op_sel:[0,1] op_sel_hi:[1,0]
	v_mov_b32_e32 v83, v70
	v_mov_b32_e32 v85, v86
	v_pk_add_f32 v[86:87], v[82:83], v[84:85]
	global_load_dwordx4 v[82:85], v[66:67], off sc1
	v_mul_f32_e32 v70, v53, v53
	v_pk_fma_f32 v[88:89], v[52:53], v[52:53], v[70:71] op_sel_hi:[1,1,0]
	v_mul_f32_e32 v70, v55, v55
	v_mov_b32_e32 v89, v90
	v_pk_fma_f32 v[90:91], v[54:55], v[54:55], v[70:71] op_sel_hi:[1,1,0]
	v_sqrt_f32_e32 v95, v69
	v_mov_b32_e32 v91, v96
	v_pk_add_f32 v[88:89], v[88:89], v[90:91]
	v_mul_f32_e32 v76, v72, v93
	v_pk_add_f32 v[86:87], v[86:87], v[88:89]
	v_fma_f32 v94, -v92, v76, v72
	v_add_f32_e32 v70, v86, v87
	ds_bpermute_b32 v71, v71, v70
	v_add_u32_e32 v86, -1, v95
	v_fma_f32 v87, -v86, v95, v69
	v_cmp_ge_f32_e64 s[2:3], 0, v87
	v_fmac_f32_e32 v76, v94, v93
	s_waitcnt lgkmcnt(0)
	v_add_f32_e32 v70, v70, v71
	ds_bpermute_b32 v71, v79, v70
	v_cndmask_b32_e64 v79, v95, v86, s[2:3]
	v_add_u32_e32 v86, 1, v95
	v_fma_f32 v72, -v92, v76, v72
	v_fma_f32 v87, -v86, v95, v69
	s_waitcnt lgkmcnt(0)
	v_add_f32_e32 v70, v70, v71
	ds_bpermute_b32 v71, v81, v70
	v_cmp_lt_f32_e64 s[2:3], 0, v87
	s_waitcnt lgkmcnt(0)
	v_add_f32_e32 v70, v70, v71
	ds_bpermute_b32 v71, v80, v70
	v_cndmask_b32_e64 v79, v79, v86, s[2:3]
	v_mul_f32_e32 v81, 0x37800000, v79
	v_cndmask_b32_e64 v79, v79, v81, s[0:1]
	v_cmp_class_f32_e64 s[0:1], v69, v73
	s_waitcnt lgkmcnt(0)
	v_add_f32_e32 v71, v70, v71
	ds_bpermute_b32 v78, v78, v71
	v_div_fmas_f32 v70, v72, v93, v76
	v_div_fixup_f32 v70, v70, v74, 1.0
	v_cndmask_b32_e64 v69, v79, v69, s[0:1]
	v_div_scale_f32 v79, s[0:1], v69, v69, 1.0
	s_waitcnt lgkmcnt(0)
	v_add_f32_e32 v71, v71, v78
	ds_bpermute_b32 v74, v77, v71
	v_rcp_f32_e32 v80, v79
	s_waitcnt lgkmcnt(0)
	v_add_f32_e32 v71, v71, v74
	v_fmac_f32_e32 v75, 0x3a800000, v71
	v_mul_f32_e32 v71, 0x4f800000, v75
	v_cmp_gt_f32_e64 s[0:1], s14, v75
	v_fma_f32 v72, -v79, v80, 1.0
	v_fmac_f32_e32 v80, v72, v80
	v_cndmask_b32_e64 v71, v75, v71, s[0:1]
	v_sqrt_f32_e32 v74, v71
	v_div_scale_f32 v72, vcc, 1.0, v69, 1.0
	v_mul_f32_e32 v76, v72, v80
	v_fma_f32 v75, -v79, v76, v72
	v_fmac_f32_e32 v76, v75, v80
	v_add_u32_e32 v75, -1, v74
	v_fma_f32 v77, -v75, v74, v71
	v_cmp_ge_f32_e64 s[2:3], 0, v77
	v_add_u32_e32 v77, 1, v74
	v_fma_f32 v72, -v79, v76, v72
	v_cndmask_b32_e64 v75, v74, v75, s[2:3]
	v_fma_f32 v74, -v77, v74, v71
	v_cmp_lt_f32_e64 s[2:3], 0, v74
	v_div_fmas_f32 v72, v72, v80, v76
	v_div_fixup_f32 v72, v72, v69, 1.0
	v_cndmask_b32_e64 v74, v75, v77, s[2:3]
	v_mul_f32_e32 v75, 0x37800000, v74
	v_cndmask_b32_e64 v74, v74, v75, s[0:1]
	v_cmp_class_f32_e64 s[0:1], v71, v73
	s_nop 1
	v_cndmask_b32_e64 v71, v74, v71, s[0:1]
	v_div_scale_f32 v73, s[0:1], v71, v71, 1.0
	v_rcp_f32_e32 v74, v73
	s_add_u32 s0, s44, s4
	s_addc_u32 s1, s45, s5
	v_pk_mul_f32 v[22:23], v[22:23], v[70:71] op_sel_hi:[1,0]
	v_fma_f32 v69, -v73, v74, 1.0
	v_fmac_f32_e32 v74, v69, v74
	v_div_scale_f32 v69, vcc, 1.0, v71, 1.0
	v_mul_f32_e32 v75, v69, v74
	v_fma_f32 v76, -v73, v75, v69
	v_fmac_f32_e32 v75, v76, v74
	v_fma_f32 v69, -v73, v75, v69
	v_div_fmas_f32 v69, v69, v74, v75
	v_pk_mul_f32 v[36:37], v[36:37], v[68:69] op_sel_hi:[1,0]
	v_pk_mul_f32 v[38:39], v[38:39], v[68:69] op_sel_hi:[1,0]
	s_waitcnt vmcnt(0)
	v_pk_mul_f32 v[36:37], v[36:37], v[82:83]
	v_pk_mul_f32 v[38:39], v[38:39], v[84:85]
	v_lshl_add_u64 v[76:77], s[0:1], 0, v[64:65]
	s_add_u32 s0, s44, s6
	global_store_dwordx4 v[76:77], v[36:39], off nt
	s_addc_u32 s1, s45, s7
	v_div_fixup_f32 v74, v69, v71, 1.0
	v_pk_mul_f32 v[36:37], v[40:41], v[70:71] op_sel_hi:[1,0]
	v_pk_mul_f32 v[38:39], v[42:43], v[70:71] op_sel_hi:[1,0]
	v_pk_mul_f32 v[36:37], v[36:37], v[82:83]
	v_pk_mul_f32 v[38:39], v[38:39], v[84:85]
	v_lshl_add_u64 v[40:41], s[0:1], 0, v[64:65]
	s_add_u32 s0, s44, s8
	global_store_dwordx4 v[40:41], v[36:39], off nt
	s_addc_u32 s1, s45, s9
	v_lshl_add_u64 v[42:43], s[0:1], 0, v[64:65]
	v_pk_mul_f32 v[36:37], v[48:49], v[72:73] op_sel_hi:[1,0]
	v_pk_mul_f32 v[38:39], v[50:51], v[72:73] op_sel_hi:[1,0]
	v_pk_mul_f32 v[36:37], v[82:83], v[36:37]
	v_pk_mul_f32 v[38:39], v[84:85], v[38:39]
	s_add_u32 s0, s44, s10
	global_store_dwordx4 v[42:43], v[36:39], off nt
	s_addc_u32 s1, s45, s11
	v_lshl_add_u64 v[48:49], s[0:1], 0, v[64:65]
	v_pk_mul_f32 v[36:37], v[60:61], v[74:75] op_sel_hi:[1,0]
	v_pk_mul_f32 v[38:39], v[62:63], v[74:75] op_sel_hi:[1,0]
	v_pk_mul_f32 v[36:37], v[82:83], v[36:37]
	v_pk_mul_f32 v[38:39], v[84:85], v[38:39]
	global_store_dwordx4 v[48:49], v[36:39], off nt
	s_nop 1
	v_mov_b64_e32 v[36:37], v[108:109]
	v_mov_b64_e32 v[38:39], v[110:111]
	v_pk_mul_f32 v[20:21], v[20:21], v[70:71] op_sel_hi:[1,0]
	v_pk_mul_f32 v[34:35], v[34:35], v[68:69] op_sel_hi:[1,0]
	v_pk_mul_f32 v[32:33], v[32:33], v[68:69] op_sel_hi:[1,0]
	v_pk_mul_f32 v[6:7], v[6:7], v[72:73] op_sel_hi:[1,0]
	v_pk_mul_f32 v[4:5], v[4:5], v[72:73] op_sel_hi:[1,0]
	v_pk_mul_f32 v[18:19], v[18:19], v[70:71] op_sel_hi:[1,0]
	v_pk_mul_f32 v[16:17], v[16:17], v[70:71] op_sel_hi:[1,0]
	v_pk_mul_f32 v[2:3], v[2:3], v[72:73] op_sel_hi:[1,0]
	v_pk_mul_f32 v[0:1], v[0:1], v[72:73] op_sel_hi:[1,0]
	v_pk_mul_f32 v[14:15], v[14:15], v[68:69] op_sel_hi:[1,0]
	v_pk_mul_f32 v[12:13], v[12:13], v[68:69] op_sel_hi:[1,0]
	v_pk_mul_f32 v[10:11], v[10:11], v[70:71] op_sel_hi:[1,0]
	v_pk_mul_f32 v[8:9], v[8:9], v[70:71] op_sel_hi:[1,0]
	s_nop 0
	v_pk_mul_f32 v[20:21], v[20:21], v[36:37]
	v_pk_mul_f32 v[22:23], v[22:23], v[38:39]
	global_store_dwordx4 v[40:41], v[20:23], off offset:1024 nt
	v_pk_mul_f32 v[32:33], v[32:33], v[36:37]
	v_pk_mul_f32 v[34:35], v[34:35], v[38:39]
	v_pk_mul_f32 v[22:23], v[26:27], v[72:73] op_sel_hi:[1,0]
	v_pk_mul_f32 v[20:21], v[24:25], v[72:73] op_sel_hi:[1,0]
	v_pk_mul_f32 v[22:23], v[22:23], v[38:39]
	v_pk_mul_f32 v[20:21], v[20:21], v[36:37]
	global_store_dwordx4 v[42:43], v[20:23], off offset:1024 nt
	global_store_dwordx4 v[76:77], v[32:35], off offset:1024 nt
	v_pk_mul_f32 v[26:27], v[30:31], v[68:69] op_sel_hi:[1,0]
	v_pk_mul_f32 v[22:23], v[58:59], v[74:75] op_sel_hi:[1,0]
	v_pk_mul_f32 v[20:21], v[56:57], v[74:75] op_sel_hi:[1,0]
	v_pk_mul_f32 v[22:23], v[38:39], v[22:23]
	v_pk_mul_f32 v[20:21], v[36:37], v[20:21]
	global_store_dwordx4 v[48:49], v[20:23], off offset:1024 nt
	s_nop 1
	v_mov_b64_e32 v[20:21], v[112:113]
	v_mov_b64_e32 v[22:23], v[114:115]
	v_pk_mul_f32 v[24:25], v[28:29], v[68:69] op_sel_hi:[1,0]
	s_nop 0
	v_pk_mul_f32 v[4:5], v[4:5], v[20:21]
	v_pk_mul_f32 v[6:7], v[6:7], v[22:23]
	global_store_dwordx4 v[42:43], v[4:7], off offset:2048 nt
	v_pk_mul_f32 v[24:25], v[24:25], v[20:21]
	v_pk_mul_f32 v[26:27], v[26:27], v[22:23]
	v_pk_mul_f32 v[6:7], v[54:55], v[74:75] op_sel_hi:[1,0]
	v_pk_mul_f32 v[4:5], v[52:53], v[74:75] op_sel_hi:[1,0]
	v_pk_mul_f32 v[16:17], v[16:17], v[20:21]
	v_pk_mul_f32 v[18:19], v[18:19], v[22:23]
	v_pk_mul_f32 v[4:5], v[4:5], v[20:21]
	v_pk_mul_f32 v[6:7], v[6:7], v[22:23]
	global_store_dwordx4 v[76:77], v[24:27], off offset:2048 nt
	global_store_dwordx4 v[40:41], v[16:19], off offset:2048 nt
	global_store_dwordx4 v[48:49], v[4:7], off offset:2048 nt
	s_nop 1
	v_mov_b64_e32 v[4:5], v[116:117]
	v_mov_b64_e32 v[6:7], v[118:119]
	s_nop 0
	v_pk_mul_f32 v[0:1], v[0:1], v[4:5]
	v_pk_mul_f32 v[2:3], v[2:3], v[6:7]
	global_store_dwordx4 v[42:43], v[0:3], off offset:3072 nt
	v_pk_mul_f32 v[12:13], v[12:13], v[4:5]
	v_pk_mul_f32 v[14:15], v[14:15], v[6:7]
	v_pk_mul_f32 v[2:3], v[46:47], v[74:75] op_sel_hi:[1,0]
	v_pk_mul_f32 v[0:1], v[44:45], v[74:75] op_sel_hi:[1,0]
	v_pk_mul_f32 v[8:9], v[8:9], v[4:5]
	v_pk_mul_f32 v[10:11], v[10:11], v[6:7]
	v_pk_mul_f32 v[0:1], v[0:1], v[4:5]
	v_pk_mul_f32 v[2:3], v[2:3], v[6:7]
	global_store_dwordx4 v[76:77], v[12:15], off offset:3072 nt
	global_store_dwordx4 v[40:41], v[8:11], off offset:3072 nt
	global_store_dwordx4 v[48:49], v[0:3], off offset:3072 nt
	s_endpgm
